# GEMM K-loops: the two MFMAs of each accumulator issued back to back (SrcC forwarding) instead of 8-accumulator sweeps; same per-accumulator order, bit-identical
# speedup vs baseline: 1.0045x; 1.0045x over previous
.LBB0_90:
	s_add_u32 s29, s76, 0xfff80080
	s_addc_u32 s30, s77, -1
	s_add_i32 s31, 0, 0x10000
	s_cmp_eq_u32 s28, 28
	s_cselect_b32 s85, s22, s30
	s_cselect_b32 s84, s23, s29
	v_add_u32_e32 v158, s31, v160
	s_cselect_b32 s55, s24, s27
	s_cselect_b32 s54, s25, s26
	s_add_i32 s29, 0, 0x14000
	ds_read_b128 v[154:157], v158
	ds_read_b128 v[180:183], v158 offset:1024
	ds_read_b128 v[184:187], v158 offset:2048
	ds_read_b128 v[188:191], v158 offset:3072
	v_add_u32_e32 v158, s29, v160
	ds_read_b128 v[192:195], v158
	ds_read_b128 v[196:199], v158 offset:1024
	ds_read_b128 v[200:203], v158 offset:2048
	ds_read_b128 v[204:207], v158 offset:3072
	v_lshl_add_u64 v[158:159], s[76:77], 0, v[152:153]
	s_add_i32 m0, s13, 0xc000
	ds_read_b128 v[208:211], v162
	ds_read_b128 v[212:215], v162 offset:1024
	ds_read_b128 v[216:219], v162 offset:2048
	ds_read_b128 v[222:225], v162 offset:3072
	ds_read_b128 v[226:229], v162 offset:4096
	ds_read_b128 v[230:233], v162 offset:5120
	ds_read_b128 v[234:237], v162 offset:6144
	ds_read_b128 v[238:241], v162 offset:7168
	global_load_lds_dwordx4 v[158:159], off
	v_lshl_add_u64 v[158:159], s[76:77], 0, v[150:151]
	s_add_i32 m0, s13, 0xe000
	s_nop 0
	global_load_lds_dwordx4 v[158:159], off
	s_waitcnt vmcnt(8)
	s_waitcnt lgkmcnt(0)
	s_barrier
	s_setprio 1
	s_waitcnt lgkmcnt(0)
	v_mfma_f32_16x16x32_bf16 v[128:131], v[154:157], v[208:211], v[128:131]
	v_mfma_f32_16x16x32_bf16 v[128:131], v[180:183], v[212:215], v[128:131]
	v_mfma_f32_16x16x32_bf16 v[124:127], v[184:187], v[208:211], v[124:127]
	v_mfma_f32_16x16x32_bf16 v[124:127], v[188:191], v[212:215], v[124:127]
	v_mfma_f32_16x16x32_bf16 v[120:123], v[154:157], v[216:219], v[120:123]
	v_mfma_f32_16x16x32_bf16 v[120:123], v[180:183], v[222:225], v[120:123]
	v_mfma_f32_16x16x32_bf16 v[112:115], v[184:187], v[216:219], v[112:115]
	v_mfma_f32_16x16x32_bf16 v[112:115], v[188:191], v[222:225], v[112:115]
	v_mfma_f32_16x16x32_bf16 v[104:107], v[154:157], v[226:229], v[104:107]
	v_mfma_f32_16x16x32_bf16 v[104:107], v[180:183], v[230:233], v[104:107]
	v_mfma_f32_16x16x32_bf16 v[96:99], v[184:187], v[226:229], v[96:99]
	v_mfma_f32_16x16x32_bf16 v[96:99], v[188:191], v[230:233], v[96:99]
	v_mfma_f32_16x16x32_bf16 v[88:91], v[154:157], v[234:237], v[88:91]
	v_mfma_f32_16x16x32_bf16 v[88:91], v[180:183], v[238:241], v[88:91]
	v_mfma_f32_16x16x32_bf16 v[80:83], v[184:187], v[234:237], v[80:83]
	v_mfma_f32_16x16x32_bf16 v[80:83], v[188:191], v[238:241], v[80:83]
	s_setprio 0
	s_setprio 1
	v_mfma_f32_16x16x32_bf16 v[116:119], v[192:195], v[208:211], v[116:119]
	v_mfma_f32_16x16x32_bf16 v[116:119], v[196:199], v[212:215], v[116:119]
	v_mfma_f32_16x16x32_bf16 v[108:111], v[200:203], v[208:211], v[108:111]
	v_mfma_f32_16x16x32_bf16 v[108:111], v[204:207], v[212:215], v[108:111]
	v_mfma_f32_16x16x32_bf16 v[100:103], v[192:195], v[216:219], v[100:103]
	v_mfma_f32_16x16x32_bf16 v[100:103], v[196:199], v[222:225], v[100:103]
	v_mfma_f32_16x16x32_bf16 v[92:95], v[200:203], v[216:219], v[92:95]
	v_mfma_f32_16x16x32_bf16 v[92:95], v[204:207], v[222:225], v[92:95]
	v_mfma_f32_16x16x32_bf16 v[84:87], v[192:195], v[226:229], v[84:87]
	v_mfma_f32_16x16x32_bf16 v[84:87], v[196:199], v[230:233], v[84:87]
	v_mfma_f32_16x16x32_bf16 v[76:79], v[200:203], v[226:229], v[76:79]
	v_mfma_f32_16x16x32_bf16 v[76:79], v[204:207], v[230:233], v[76:79]
	v_mfma_f32_16x16x32_bf16 v[72:75], v[192:195], v[234:237], v[72:75]
	v_mfma_f32_16x16x32_bf16 v[72:75], v[196:199], v[238:241], v[72:75]
	v_mfma_f32_16x16x32_bf16 v[68:71], v[200:203], v[234:237], v[68:71]
	v_mfma_f32_16x16x32_bf16 v[68:71], v[204:207], v[238:241], v[68:71]
	s_setprio 0
	s_barrier
	s_add_i32 s30, s31, s12
	v_lshl_add_u64 v[158:159], s[54:55], 0, v[34:35]
	s_mov_b32 m0, s30
	ds_read_b128 v[208:211], v162 offset:16384
	ds_read_b128 v[212:215], v162 offset:17408
	ds_read_b128 v[216:219], v162 offset:18432
	ds_read_b128 v[222:225], v162 offset:19456
	ds_read_b128 v[226:229], v162 offset:20480
	ds_read_b128 v[230:233], v162 offset:21504
	ds_read_b128 v[234:237], v162 offset:22528
	ds_read_b128 v[238:241], v162 offset:23552
	global_load_lds_dwordx4 v[158:159], off
	s_add_i32 m0, s30, 0x2000
	s_add_u32 s30, s54, 0x80000
	v_lshl_add_u64 v[242:243], s[54:55], 0, v[146:147]
	s_addc_u32 s31, s55, 0
	s_add_i32 s29, s29, s12
	global_load_lds_dwordx4 v[242:243], off
	v_lshl_add_u64 v[244:245], s[30:31], 0, v[34:35]
	s_mov_b32 m0, s29
	v_lshl_add_u64 v[246:247], s[84:85], 0, v[144:145]
	global_load_lds_dwordx4 v[244:245], off
	v_lshl_add_u64 v[244:245], s[30:31], 0, v[146:147]
	s_add_i32 m0, s29, 0x2000
	s_nop 0
	global_load_lds_dwordx4 v[244:245], off
	v_lshl_add_u64 v[244:245], s[84:85], 0, v[142:143]
	s_mov_b32 m0, s13
	s_nop 0
	global_load_lds_dwordx4 v[244:245], off
	s_mov_b32 m0, s14
	s_nop 0
	global_load_lds_dwordx4 v[246:247], off
	s_waitcnt vmcnt(8)
	s_waitcnt lgkmcnt(0)
	s_barrier
	s_setprio 1
	s_waitcnt lgkmcnt(0)
	v_mfma_f32_16x16x32_bf16 v[64:67], v[154:157], v[208:211], v[64:67]
	v_mfma_f32_16x16x32_bf16 v[64:67], v[180:183], v[212:215], v[64:67]
	v_mfma_f32_16x16x32_bf16 v[60:63], v[184:187], v[208:211], v[60:63]
	v_mfma_f32_16x16x32_bf16 v[60:63], v[188:191], v[212:215], v[60:63]
	v_mfma_f32_16x16x32_bf16 v[56:59], v[154:157], v[216:219], v[56:59]
	v_mfma_f32_16x16x32_bf16 v[56:59], v[180:183], v[222:225], v[56:59]
	v_mfma_f32_16x16x32_bf16 v[48:51], v[184:187], v[216:219], v[48:51]
	v_mfma_f32_16x16x32_bf16 v[48:51], v[188:191], v[222:225], v[48:51]
	v_mfma_f32_16x16x32_bf16 v[40:43], v[154:157], v[226:229], v[40:43]
	v_mfma_f32_16x16x32_bf16 v[40:43], v[180:183], v[230:233], v[40:43]
	v_mfma_f32_16x16x32_bf16 v[30:33], v[184:187], v[226:229], v[30:33]
	v_mfma_f32_16x16x32_bf16 v[30:33], v[188:191], v[230:233], v[30:33]
	v_mfma_f32_16x16x32_bf16 v[22:25], v[154:157], v[234:237], v[22:25]
	v_mfma_f32_16x16x32_bf16 v[22:25], v[180:183], v[238:241], v[22:25]
	v_mfma_f32_16x16x32_bf16 v[14:17], v[184:187], v[234:237], v[14:17]
	v_mfma_f32_16x16x32_bf16 v[14:17], v[188:191], v[238:241], v[14:17]
	s_setprio 0
	s_setprio 1
	v_mfma_f32_16x16x32_bf16 v[52:55], v[192:195], v[208:211], v[52:55]
	v_mfma_f32_16x16x32_bf16 v[52:55], v[196:199], v[212:215], v[52:55]
	v_mfma_f32_16x16x32_bf16 v[44:47], v[200:203], v[208:211], v[44:47]
	v_mfma_f32_16x16x32_bf16 v[44:47], v[204:207], v[212:215], v[44:47]
	v_mfma_f32_16x16x32_bf16 v[36:39], v[192:195], v[216:219], v[36:39]
	v_mfma_f32_16x16x32_bf16 v[36:39], v[196:199], v[222:225], v[36:39]
	v_mfma_f32_16x16x32_bf16 v[26:29], v[200:203], v[216:219], v[26:29]
	v_mfma_f32_16x16x32_bf16 v[26:29], v[204:207], v[222:225], v[26:29]
	v_mfma_f32_16x16x32_bf16 v[18:21], v[192:195], v[226:229], v[18:21]
	v_mfma_f32_16x16x32_bf16 v[18:21], v[196:199], v[230:233], v[18:21]
	v_mfma_f32_16x16x32_bf16 v[10:13], v[200:203], v[226:229], v[10:13]
	v_mfma_f32_16x16x32_bf16 v[10:13], v[204:207], v[230:233], v[10:13]
	v_mfma_f32_16x16x32_bf16 v[6:9], v[192:195], v[234:237], v[6:9]
	v_mfma_f32_16x16x32_bf16 v[6:9], v[196:199], v[238:241], v[6:9]
	v_mfma_f32_16x16x32_bf16 v[2:5], v[200:203], v[234:237], v[2:5]
	v_mfma_f32_16x16x32_bf16 v[2:5], v[204:207], v[238:241], v[2:5]
	s_setprio 0
	s_barrier
	s_add_i32 s29, 0, 0x18000
	v_add_u32_e32 v163, s29, v160
	s_add_i32 s39, 0, 0x1c000
	ds_read_b128 v[154:157], v163
	ds_read_b128 v[180:183], v163 offset:1024
	ds_read_b128 v[184:187], v163 offset:2048
	ds_read_b128 v[188:191], v163 offset:3072
	v_add_u32_e32 v163, s39, v160
	ds_read_b128 v[192:195], v163
	ds_read_b128 v[196:199], v163 offset:1024
	ds_read_b128 v[200:203], v163 offset:2048
	ds_read_b128 v[204:207], v163 offset:3072
	s_add_u32 s30, s84, 0x80000
	s_addc_u32 s31, s85, 0
	s_mov_b32 m0, s15
	v_lshl_add_u64 v[248:249], s[30:31], 0, v[142:143]
	ds_read_b128 v[208:211], v162 offset:32768
	ds_read_b128 v[212:215], v162 offset:33792
	ds_read_b128 v[216:219], v162 offset:34816
	ds_read_b128 v[222:225], v162 offset:35840
	ds_read_b128 v[226:229], v162 offset:36864
	ds_read_b128 v[230:233], v162 offset:37888
	ds_read_b128 v[234:237], v162 offset:38912
	ds_read_b128 v[238:241], v162 offset:39936
	global_load_lds_dwordx4 v[248:249], off
	v_lshl_add_u64 v[248:249], s[30:31], 0, v[144:145]
	s_mov_b32 m0, s16
	s_nop 0
	global_load_lds_dwordx4 v[248:249], off
	s_waitcnt vmcnt(8)
	s_waitcnt lgkmcnt(0)
	s_barrier
	s_setprio 1
	s_waitcnt lgkmcnt(0)
	v_mfma_f32_16x16x32_bf16 v[128:131], v[154:157], v[208:211], v[128:131]
	v_mfma_f32_16x16x32_bf16 v[128:131], v[180:183], v[212:215], v[128:131]
	v_mfma_f32_16x16x32_bf16 v[124:127], v[184:187], v[208:211], v[124:127]
	v_mfma_f32_16x16x32_bf16 v[124:127], v[188:191], v[212:215], v[124:127]
	v_mfma_f32_16x16x32_bf16 v[120:123], v[154:157], v[216:219], v[120:123]
	v_mfma_f32_16x16x32_bf16 v[120:123], v[180:183], v[222:225], v[120:123]
	v_mfma_f32_16x16x32_bf16 v[112:115], v[184:187], v[216:219], v[112:115]
	v_mfma_f32_16x16x32_bf16 v[112:115], v[188:191], v[222:225], v[112:115]
	v_mfma_f32_16x16x32_bf16 v[104:107], v[154:157], v[226:229], v[104:107]
	v_mfma_f32_16x16x32_bf16 v[104:107], v[180:183], v[230:233], v[104:107]
	v_mfma_f32_16x16x32_bf16 v[96:99], v[184:187], v[226:229], v[96:99]
	v_mfma_f32_16x16x32_bf16 v[96:99], v[188:191], v[230:233], v[96:99]
	v_mfma_f32_16x16x32_bf16 v[88:91], v[154:157], v[234:237], v[88:91]
	v_mfma_f32_16x16x32_bf16 v[88:91], v[180:183], v[238:241], v[88:91]
	v_mfma_f32_16x16x32_bf16 v[80:83], v[184:187], v[234:237], v[80:83]
	v_mfma_f32_16x16x32_bf16 v[80:83], v[188:191], v[238:241], v[80:83]
	s_setprio 0
	s_setprio 1
	v_mfma_f32_16x16x32_bf16 v[116:119], v[192:195], v[208:211], v[116:119]
	v_mfma_f32_16x16x32_bf16 v[116:119], v[196:199], v[212:215], v[116:119]
	v_mfma_f32_16x16x32_bf16 v[108:111], v[200:203], v[208:211], v[108:111]
	v_mfma_f32_16x16x32_bf16 v[108:111], v[204:207], v[212:215], v[108:111]
	v_mfma_f32_16x16x32_bf16 v[100:103], v[192:195], v[216:219], v[100:103]
	v_mfma_f32_16x16x32_bf16 v[100:103], v[196:199], v[222:225], v[100:103]
	v_mfma_f32_16x16x32_bf16 v[92:95], v[200:203], v[216:219], v[92:95]
	v_mfma_f32_16x16x32_bf16 v[92:95], v[204:207], v[222:225], v[92:95]
	v_mfma_f32_16x16x32_bf16 v[84:87], v[192:195], v[226:229], v[84:87]
	v_mfma_f32_16x16x32_bf16 v[84:87], v[196:199], v[230:233], v[84:87]
	v_mfma_f32_16x16x32_bf16 v[76:79], v[200:203], v[226:229], v[76:79]
	v_mfma_f32_16x16x32_bf16 v[76:79], v[204:207], v[230:233], v[76:79]
	v_mfma_f32_16x16x32_bf16 v[72:75], v[192:195], v[234:237], v[72:75]
	v_mfma_f32_16x16x32_bf16 v[72:75], v[196:199], v[238:241], v[72:75]
	v_mfma_f32_16x16x32_bf16 v[68:71], v[200:203], v[234:237], v[68:71]
	v_mfma_f32_16x16x32_bf16 v[68:71], v[204:207], v[238:241], v[68:71]
	s_setprio 0
	s_barrier
	s_add_i32 s29, s29, s12
	v_lshl_add_u64 v[158:159], v[158:159], 0, s[78:79]
	s_mov_b32 m0, s29
	ds_read_b128 v[208:211], v162 offset:49152
	ds_read_b128 v[212:215], v162 offset:50176
	ds_read_b128 v[216:219], v162 offset:51200
	ds_read_b128 v[222:225], v162 offset:52224
	ds_read_b128 v[226:229], v162 offset:53248
	ds_read_b128 v[230:233], v162 offset:54272
	ds_read_b128 v[234:237], v162 offset:55296
	ds_read_b128 v[238:241], v162 offset:56320
	global_load_lds_dwordx4 v[158:159], off
	s_add_i32 m0, s29, 0x2000
	s_add_u32 s30, s54, 0x80080
	v_lshl_add_u64 v[158:159], v[242:243], 0, s[78:79]
	s_addc_u32 s31, s55, 0
	s_add_i32 s29, s39, s12
	global_load_lds_dwordx4 v[158:159], off
	v_lshl_add_u64 v[158:159], s[30:31], 0, v[34:35]
	s_mov_b32 m0, s29
	s_nop 0
	global_load_lds_dwordx4 v[158:159], off
	v_lshl_add_u64 v[158:159], s[30:31], 0, v[146:147]
	s_add_i32 m0, s29, 0x2000
	s_nop 0
	global_load_lds_dwordx4 v[158:159], off
	v_lshl_add_u64 v[158:159], v[244:245], 0, s[78:79]
	s_mov_b32 m0, s18
	s_nop 0
	global_load_lds_dwordx4 v[158:159], off
	v_lshl_add_u64 v[158:159], v[246:247], 0, s[78:79]
	s_mov_b32 m0, s19
	s_nop 0
	global_load_lds_dwordx4 v[158:159], off
	s_waitcnt vmcnt(8)
	s_waitcnt lgkmcnt(0)
	s_barrier
	s_setprio 1
	s_waitcnt lgkmcnt(0)
	v_mfma_f32_16x16x32_bf16 v[64:67], v[154:157], v[208:211], v[64:67]
	v_mfma_f32_16x16x32_bf16 v[64:67], v[180:183], v[212:215], v[64:67]
	v_mfma_f32_16x16x32_bf16 v[60:63], v[184:187], v[208:211], v[60:63]
	v_mfma_f32_16x16x32_bf16 v[60:63], v[188:191], v[212:215], v[60:63]
	v_mfma_f32_16x16x32_bf16 v[56:59], v[154:157], v[216:219], v[56:59]
	v_mfma_f32_16x16x32_bf16 v[56:59], v[180:183], v[222:225], v[56:59]
	v_mfma_f32_16x16x32_bf16 v[48:51], v[184:187], v[216:219], v[48:51]
	v_mfma_f32_16x16x32_bf16 v[48:51], v[188:191], v[222:225], v[48:51]
	v_mfma_f32_16x16x32_bf16 v[40:43], v[154:157], v[226:229], v[40:43]
	v_mfma_f32_16x16x32_bf16 v[40:43], v[180:183], v[230:233], v[40:43]
	v_mfma_f32_16x16x32_bf16 v[30:33], v[184:187], v[226:229], v[30:33]
	v_mfma_f32_16x16x32_bf16 v[30:33], v[188:191], v[230:233], v[30:33]
	v_mfma_f32_16x16x32_bf16 v[22:25], v[154:157], v[234:237], v[22:25]
	v_mfma_f32_16x16x32_bf16 v[22:25], v[180:183], v[238:241], v[22:25]
	v_mfma_f32_16x16x32_bf16 v[14:17], v[184:187], v[234:237], v[14:17]
	v_mfma_f32_16x16x32_bf16 v[14:17], v[188:191], v[238:241], v[14:17]
	s_setprio 0
	s_setprio 1
	v_mfma_f32_16x16x32_bf16 v[52:55], v[192:195], v[208:211], v[52:55]
	v_mfma_f32_16x16x32_bf16 v[52:55], v[196:199], v[212:215], v[52:55]
	v_mfma_f32_16x16x32_bf16 v[44:47], v[200:203], v[208:211], v[44:47]
	v_mfma_f32_16x16x32_bf16 v[44:47], v[204:207], v[212:215], v[44:47]
	v_mfma_f32_16x16x32_bf16 v[36:39], v[192:195], v[216:219], v[36:39]
	v_mfma_f32_16x16x32_bf16 v[36:39], v[196:199], v[222:225], v[36:39]
	v_mfma_f32_16x16x32_bf16 v[26:29], v[200:203], v[216:219], v[26:29]
	v_mfma_f32_16x16x32_bf16 v[26:29], v[204:207], v[222:225], v[26:29]
	v_mfma_f32_16x16x32_bf16 v[18:21], v[192:195], v[226:229], v[18:21]
	v_mfma_f32_16x16x32_bf16 v[18:21], v[196:199], v[230:233], v[18:21]
	v_mfma_f32_16x16x32_bf16 v[10:13], v[200:203], v[226:229], v[10:13]
	v_mfma_f32_16x16x32_bf16 v[10:13], v[204:207], v[230:233], v[10:13]
	v_mfma_f32_16x16x32_bf16 v[6:9], v[192:195], v[234:237], v[6:9]
	v_mfma_f32_16x16x32_bf16 v[6:9], v[196:199], v[238:241], v[6:9]
	v_mfma_f32_16x16x32_bf16 v[2:5], v[200:203], v[234:237], v[2:5]
	v_mfma_f32_16x16x32_bf16 v[2:5], v[204:207], v[238:241], v[2:5]
	s_setprio 0
	s_barrier
	s_add_i32 s28, s28, 2
	s_add_u32 s26, s26, 0x100
	s_addc_u32 s27, s27, 0
	s_add_u32 s76, s76, 0x100
	s_addc_u32 s77, s77, 0
	s_cmp_gt_u32 s28, 29
	s_cbranch_scc0 .LBB0_90
	s_and_b64 vcc, exec, s[52:53]
	s_cbranch_vccz .LBB0_93
	s_barrier

.LBB0_844:
	s_add_u32 s27, s62, 0xffe00080
	s_addc_u32 s28, s63, -1
	s_add_i32 s29, 0, 0x10000
	s_cmp_eq_u32 s26, 28
	s_cselect_b32 s67, s20, s28
	s_cselect_b32 s66, s21, s27
	v_add_u32_e32 v152, s29, v154
	s_cselect_b32 s55, s22, s25
	s_cselect_b32 s54, s23, s24
	s_add_i32 s27, 0, 0x14000
	ds_read_b128 v[158:161], v152
	ds_read_b128 v[180:183], v152 offset:1024
	ds_read_b128 v[184:187], v152 offset:2048
	ds_read_b128 v[188:191], v152 offset:3072
	v_add_u32_e32 v152, s27, v154
	ds_read_b128 v[192:195], v152
	ds_read_b128 v[196:199], v152 offset:1024
	ds_read_b128 v[200:203], v152 offset:2048
	ds_read_b128 v[204:207], v152 offset:3072
	v_lshl_add_u64 v[152:153], s[62:63], 0, v[150:151]
	s_add_i32 m0, s12, 0xc000
	ds_read_b128 v[208:211], v156
	ds_read_b128 v[212:215], v156 offset:1024
	ds_read_b128 v[216:219], v156 offset:2048
	ds_read_b128 v[222:225], v156 offset:3072
	ds_read_b128 v[226:229], v156 offset:4096
	ds_read_b128 v[230:233], v156 offset:5120
	ds_read_b128 v[234:237], v156 offset:6144
	ds_read_b128 v[238:241], v156 offset:7168
	global_load_lds_dwordx4 v[152:153], off
	v_lshl_add_u64 v[152:153], s[62:63], 0, v[148:149]
	s_add_i32 m0, s12, 0xe000
	s_nop 0
	global_load_lds_dwordx4 v[152:153], off
	s_waitcnt vmcnt(8)
	s_waitcnt lgkmcnt(0)
	s_barrier
	s_setprio 1
	s_waitcnt lgkmcnt(0)
	v_mfma_f32_16x16x32_bf16 v[128:131], v[158:161], v[208:211], v[128:131]
	v_mfma_f32_16x16x32_bf16 v[128:131], v[180:183], v[212:215], v[128:131]
	v_mfma_f32_16x16x32_bf16 v[124:127], v[184:187], v[208:211], v[124:127]
	v_mfma_f32_16x16x32_bf16 v[124:127], v[188:191], v[212:215], v[124:127]
	v_mfma_f32_16x16x32_bf16 v[120:123], v[158:161], v[216:219], v[120:123]
	v_mfma_f32_16x16x32_bf16 v[120:123], v[180:183], v[222:225], v[120:123]
	v_mfma_f32_16x16x32_bf16 v[112:115], v[184:187], v[216:219], v[112:115]
	v_mfma_f32_16x16x32_bf16 v[112:115], v[188:191], v[222:225], v[112:115]
	v_mfma_f32_16x16x32_bf16 v[104:107], v[158:161], v[226:229], v[104:107]
	v_mfma_f32_16x16x32_bf16 v[104:107], v[180:183], v[230:233], v[104:107]
	v_mfma_f32_16x16x32_bf16 v[96:99], v[184:187], v[226:229], v[96:99]
	v_mfma_f32_16x16x32_bf16 v[96:99], v[188:191], v[230:233], v[96:99]
	v_mfma_f32_16x16x32_bf16 v[88:91], v[158:161], v[234:237], v[88:91]
	v_mfma_f32_16x16x32_bf16 v[88:91], v[180:183], v[238:241], v[88:91]
	v_mfma_f32_16x16x32_bf16 v[80:83], v[184:187], v[234:237], v[80:83]
	v_mfma_f32_16x16x32_bf16 v[80:83], v[188:191], v[238:241], v[80:83]
	s_setprio 0
	s_setprio 1
	v_mfma_f32_16x16x32_bf16 v[116:119], v[192:195], v[208:211], v[116:119]
	v_mfma_f32_16x16x32_bf16 v[116:119], v[196:199], v[212:215], v[116:119]
	v_mfma_f32_16x16x32_bf16 v[108:111], v[200:203], v[208:211], v[108:111]
	v_mfma_f32_16x16x32_bf16 v[108:111], v[204:207], v[212:215], v[108:111]
	v_mfma_f32_16x16x32_bf16 v[100:103], v[192:195], v[216:219], v[100:103]
	v_mfma_f32_16x16x32_bf16 v[100:103], v[196:199], v[222:225], v[100:103]
	v_mfma_f32_16x16x32_bf16 v[92:95], v[200:203], v[216:219], v[92:95]
	v_mfma_f32_16x16x32_bf16 v[92:95], v[204:207], v[222:225], v[92:95]
	v_mfma_f32_16x16x32_bf16 v[84:87], v[192:195], v[226:229], v[84:87]
	v_mfma_f32_16x16x32_bf16 v[84:87], v[196:199], v[230:233], v[84:87]
	v_mfma_f32_16x16x32_bf16 v[76:79], v[200:203], v[226:229], v[76:79]
	v_mfma_f32_16x16x32_bf16 v[76:79], v[204:207], v[230:233], v[76:79]
	v_mfma_f32_16x16x32_bf16 v[72:75], v[192:195], v[234:237], v[72:75]
	v_mfma_f32_16x16x32_bf16 v[72:75], v[196:199], v[238:241], v[72:75]
	v_mfma_f32_16x16x32_bf16 v[68:71], v[200:203], v[234:237], v[68:71]
	v_mfma_f32_16x16x32_bf16 v[68:71], v[204:207], v[238:241], v[68:71]
	s_setprio 0
	s_barrier
	s_add_i32 s28, s29, s11
	v_lshl_add_u64 v[152:153], s[54:55], 0, v[34:35]
	s_mov_b32 m0, s28
	ds_read_b128 v[208:211], v156 offset:16384
	ds_read_b128 v[212:215], v156 offset:17408
	ds_read_b128 v[216:219], v156 offset:18432
	ds_read_b128 v[222:225], v156 offset:19456
	ds_read_b128 v[226:229], v156 offset:20480
	ds_read_b128 v[230:233], v156 offset:21504
	ds_read_b128 v[234:237], v156 offset:22528
	ds_read_b128 v[238:241], v156 offset:23552
	global_load_lds_dwordx4 v[152:153], off
	s_add_i32 m0, s28, 0x2000
	s_add_u32 s28, s54, 0x80000
	v_lshl_add_u64 v[162:163], s[54:55], 0, v[146:147]
	s_addc_u32 s29, s55, 0
	s_add_i32 s27, s27, s11
	global_load_lds_dwordx4 v[162:163], off
	v_lshl_add_u64 v[242:243], s[28:29], 0, v[34:35]
	s_mov_b32 m0, s27
	v_lshl_add_u64 v[244:245], s[66:67], 0, v[144:145]
	global_load_lds_dwordx4 v[242:243], off
	v_lshl_add_u64 v[242:243], s[28:29], 0, v[146:147]
	s_add_i32 m0, s27, 0x2000
	s_nop 0
	global_load_lds_dwordx4 v[242:243], off
	v_lshl_add_u64 v[242:243], s[66:67], 0, v[142:143]
	s_mov_b32 m0, s12
	s_nop 0
	global_load_lds_dwordx4 v[242:243], off
	s_mov_b32 m0, s13
	s_nop 0
	global_load_lds_dwordx4 v[244:245], off
	s_waitcnt vmcnt(8)
	s_waitcnt lgkmcnt(0)
	s_barrier
	s_setprio 1
	s_waitcnt lgkmcnt(0)
	v_mfma_f32_16x16x32_bf16 v[64:67], v[158:161], v[208:211], v[64:67]
	v_mfma_f32_16x16x32_bf16 v[64:67], v[180:183], v[212:215], v[64:67]
	v_mfma_f32_16x16x32_bf16 v[60:63], v[184:187], v[208:211], v[60:63]
	v_mfma_f32_16x16x32_bf16 v[60:63], v[188:191], v[212:215], v[60:63]
	v_mfma_f32_16x16x32_bf16 v[56:59], v[158:161], v[216:219], v[56:59]
	v_mfma_f32_16x16x32_bf16 v[56:59], v[180:183], v[222:225], v[56:59]
	v_mfma_f32_16x16x32_bf16 v[48:51], v[184:187], v[216:219], v[48:51]
	v_mfma_f32_16x16x32_bf16 v[48:51], v[188:191], v[222:225], v[48:51]
	v_mfma_f32_16x16x32_bf16 v[40:43], v[158:161], v[226:229], v[40:43]
	v_mfma_f32_16x16x32_bf16 v[40:43], v[180:183], v[230:233], v[40:43]
	v_mfma_f32_16x16x32_bf16 v[30:33], v[184:187], v[226:229], v[30:33]
	v_mfma_f32_16x16x32_bf16 v[30:33], v[188:191], v[230:233], v[30:33]
	v_mfma_f32_16x16x32_bf16 v[22:25], v[158:161], v[234:237], v[22:25]
	v_mfma_f32_16x16x32_bf16 v[22:25], v[180:183], v[238:241], v[22:25]
	v_mfma_f32_16x16x32_bf16 v[14:17], v[184:187], v[234:237], v[14:17]
	v_mfma_f32_16x16x32_bf16 v[14:17], v[188:191], v[238:241], v[14:17]
	s_setprio 0
	s_setprio 1
	v_mfma_f32_16x16x32_bf16 v[52:55], v[192:195], v[208:211], v[52:55]
	v_mfma_f32_16x16x32_bf16 v[52:55], v[196:199], v[212:215], v[52:55]
	v_mfma_f32_16x16x32_bf16 v[44:47], v[200:203], v[208:211], v[44:47]
	v_mfma_f32_16x16x32_bf16 v[44:47], v[204:207], v[212:215], v[44:47]
	v_mfma_f32_16x16x32_bf16 v[36:39], v[192:195], v[216:219], v[36:39]
	v_mfma_f32_16x16x32_bf16 v[36:39], v[196:199], v[222:225], v[36:39]
	v_mfma_f32_16x16x32_bf16 v[26:29], v[200:203], v[216:219], v[26:29]
	v_mfma_f32_16x16x32_bf16 v[26:29], v[204:207], v[222:225], v[26:29]
	v_mfma_f32_16x16x32_bf16 v[18:21], v[192:195], v[226:229], v[18:21]
	v_mfma_f32_16x16x32_bf16 v[18:21], v[196:199], v[230:233], v[18:21]
	v_mfma_f32_16x16x32_bf16 v[10:13], v[200:203], v[226:229], v[10:13]
	v_mfma_f32_16x16x32_bf16 v[10:13], v[204:207], v[230:233], v[10:13]
	v_mfma_f32_16x16x32_bf16 v[6:9], v[192:195], v[234:237], v[6:9]
	v_mfma_f32_16x16x32_bf16 v[6:9], v[196:199], v[238:241], v[6:9]
	v_mfma_f32_16x16x32_bf16 v[2:5], v[200:203], v[234:237], v[2:5]
	v_mfma_f32_16x16x32_bf16 v[2:5], v[204:207], v[238:241], v[2:5]
	s_setprio 0
	s_barrier
	s_add_i32 s27, 0, 0x18000
	v_add_u32_e32 v157, s27, v154
	s_add_i32 s30, 0, 0x1c000
	ds_read_b128 v[158:161], v157
	ds_read_b128 v[180:183], v157 offset:1024
	ds_read_b128 v[184:187], v157 offset:2048
	ds_read_b128 v[188:191], v157 offset:3072
	v_add_u32_e32 v157, s30, v154
	ds_read_b128 v[192:195], v157
	ds_read_b128 v[196:199], v157 offset:1024
	ds_read_b128 v[200:203], v157 offset:2048
	ds_read_b128 v[204:207], v157 offset:3072
	s_add_u32 s28, s66, 0x200000
	s_addc_u32 s29, s67, 0
	s_mov_b32 m0, s14
	v_lshl_add_u64 v[246:247], s[28:29], 0, v[142:143]
	ds_read_b128 v[208:211], v156 offset:32768
	ds_read_b128 v[212:215], v156 offset:33792
	ds_read_b128 v[216:219], v156 offset:34816
	ds_read_b128 v[222:225], v156 offset:35840
	ds_read_b128 v[226:229], v156 offset:36864
	ds_read_b128 v[230:233], v156 offset:37888
	ds_read_b128 v[234:237], v156 offset:38912
	ds_read_b128 v[238:241], v156 offset:39936
	global_load_lds_dwordx4 v[246:247], off
	v_lshl_add_u64 v[246:247], s[28:29], 0, v[144:145]
	s_mov_b32 m0, s15
	s_nop 0
	global_load_lds_dwordx4 v[246:247], off
	s_waitcnt vmcnt(8)
	s_waitcnt lgkmcnt(0)
	s_barrier
	s_setprio 1
	s_waitcnt lgkmcnt(0)
	v_mfma_f32_16x16x32_bf16 v[128:131], v[158:161], v[208:211], v[128:131]
	v_mfma_f32_16x16x32_bf16 v[128:131], v[180:183], v[212:215], v[128:131]
	v_mfma_f32_16x16x32_bf16 v[124:127], v[184:187], v[208:211], v[124:127]
	v_mfma_f32_16x16x32_bf16 v[124:127], v[188:191], v[212:215], v[124:127]
	v_mfma_f32_16x16x32_bf16 v[120:123], v[158:161], v[216:219], v[120:123]
	v_mfma_f32_16x16x32_bf16 v[120:123], v[180:183], v[222:225], v[120:123]
	v_mfma_f32_16x16x32_bf16 v[112:115], v[184:187], v[216:219], v[112:115]
	v_mfma_f32_16x16x32_bf16 v[112:115], v[188:191], v[222:225], v[112:115]
	v_mfma_f32_16x16x32_bf16 v[104:107], v[158:161], v[226:229], v[104:107]
	v_mfma_f32_16x16x32_bf16 v[104:107], v[180:183], v[230:233], v[104:107]
	v_mfma_f32_16x16x32_bf16 v[96:99], v[184:187], v[226:229], v[96:99]
	v_mfma_f32_16x16x32_bf16 v[96:99], v[188:191], v[230:233], v[96:99]
	v_mfma_f32_16x16x32_bf16 v[88:91], v[158:161], v[234:237], v[88:91]
	v_mfma_f32_16x16x32_bf16 v[88:91], v[180:183], v[238:241], v[88:91]
	v_mfma_f32_16x16x32_bf16 v[80:83], v[184:187], v[234:237], v[80:83]
	v_mfma_f32_16x16x32_bf16 v[80:83], v[188:191], v[238:241], v[80:83]
	s_setprio 0
	s_setprio 1
	v_mfma_f32_16x16x32_bf16 v[116:119], v[192:195], v[208:211], v[116:119]
	v_mfma_f32_16x16x32_bf16 v[116:119], v[196:199], v[212:215], v[116:119]
	v_mfma_f32_16x16x32_bf16 v[108:111], v[200:203], v[208:211], v[108:111]
	v_mfma_f32_16x16x32_bf16 v[108:111], v[204:207], v[212:215], v[108:111]
	v_mfma_f32_16x16x32_bf16 v[100:103], v[192:195], v[216:219], v[100:103]
	v_mfma_f32_16x16x32_bf16 v[100:103], v[196:199], v[222:225], v[100:103]
	v_mfma_f32_16x16x32_bf16 v[92:95], v[200:203], v[216:219], v[92:95]
	v_mfma_f32_16x16x32_bf16 v[92:95], v[204:207], v[222:225], v[92:95]
	v_mfma_f32_16x16x32_bf16 v[84:87], v[192:195], v[226:229], v[84:87]
	v_mfma_f32_16x16x32_bf16 v[84:87], v[196:199], v[230:233], v[84:87]
	v_mfma_f32_16x16x32_bf16 v[76:79], v[200:203], v[226:229], v[76:79]
	v_mfma_f32_16x16x32_bf16 v[76:79], v[204:207], v[230:233], v[76:79]
	v_mfma_f32_16x16x32_bf16 v[72:75], v[192:195], v[234:237], v[72:75]
	v_mfma_f32_16x16x32_bf16 v[72:75], v[196:199], v[238:241], v[72:75]
	v_mfma_f32_16x16x32_bf16 v[68:71], v[200:203], v[234:237], v[68:71]
	v_mfma_f32_16x16x32_bf16 v[68:71], v[204:207], v[238:241], v[68:71]
	s_setprio 0
	s_barrier
	s_add_i32 s27, s27, s11
	v_lshl_add_u64 v[152:153], v[152:153], 0, s[78:79]
	s_mov_b32 m0, s27
	ds_read_b128 v[208:211], v156 offset:49152
	ds_read_b128 v[212:215], v156 offset:50176
	ds_read_b128 v[216:219], v156 offset:51200
	ds_read_b128 v[222:225], v156 offset:52224
	ds_read_b128 v[226:229], v156 offset:53248
	ds_read_b128 v[230:233], v156 offset:54272
	ds_read_b128 v[234:237], v156 offset:55296
	ds_read_b128 v[238:241], v156 offset:56320
	global_load_lds_dwordx4 v[152:153], off
	s_add_i32 m0, s27, 0x2000
	s_add_u32 s28, s54, 0x80080
	v_lshl_add_u64 v[152:153], v[162:163], 0, s[78:79]
	s_addc_u32 s29, s55, 0
	s_add_i32 s27, s30, s11
	global_load_lds_dwordx4 v[152:153], off
	v_lshl_add_u64 v[152:153], s[28:29], 0, v[34:35]
	s_mov_b32 m0, s27
	s_nop 0
	global_load_lds_dwordx4 v[152:153], off
	v_lshl_add_u64 v[152:153], s[28:29], 0, v[146:147]
	s_add_i32 m0, s27, 0x2000
	s_nop 0
	global_load_lds_dwordx4 v[152:153], off
	v_lshl_add_u64 v[152:153], v[242:243], 0, s[78:79]
	s_mov_b32 m0, s16
	s_nop 0
	global_load_lds_dwordx4 v[152:153], off
	v_lshl_add_u64 v[152:153], v[244:245], 0, s[78:79]
	s_mov_b32 m0, s17
	s_nop 0
	global_load_lds_dwordx4 v[152:153], off
	s_waitcnt vmcnt(8)
	s_waitcnt lgkmcnt(0)
	s_barrier
	s_setprio 1
	s_waitcnt lgkmcnt(0)
	v_mfma_f32_16x16x32_bf16 v[64:67], v[158:161], v[208:211], v[64:67]
	v_mfma_f32_16x16x32_bf16 v[64:67], v[180:183], v[212:215], v[64:67]
	v_mfma_f32_16x16x32_bf16 v[60:63], v[184:187], v[208:211], v[60:63]
	v_mfma_f32_16x16x32_bf16 v[60:63], v[188:191], v[212:215], v[60:63]
	v_mfma_f32_16x16x32_bf16 v[56:59], v[158:161], v[216:219], v[56:59]
	v_mfma_f32_16x16x32_bf16 v[56:59], v[180:183], v[222:225], v[56:59]
	v_mfma_f32_16x16x32_bf16 v[48:51], v[184:187], v[216:219], v[48:51]
	v_mfma_f32_16x16x32_bf16 v[48:51], v[188:191], v[222:225], v[48:51]
	v_mfma_f32_16x16x32_bf16 v[40:43], v[158:161], v[226:229], v[40:43]
	v_mfma_f32_16x16x32_bf16 v[40:43], v[180:183], v[230:233], v[40:43]
	v_mfma_f32_16x16x32_bf16 v[30:33], v[184:187], v[226:229], v[30:33]
	v_mfma_f32_16x16x32_bf16 v[30:33], v[188:191], v[230:233], v[30:33]
	v_mfma_f32_16x16x32_bf16 v[22:25], v[158:161], v[234:237], v[22:25]
	v_mfma_f32_16x16x32_bf16 v[22:25], v[180:183], v[238:241], v[22:25]
	v_mfma_f32_16x16x32_bf16 v[14:17], v[184:187], v[234:237], v[14:17]
	v_mfma_f32_16x16x32_bf16 v[14:17], v[188:191], v[238:241], v[14:17]
	s_setprio 0
	s_setprio 1
	v_mfma_f32_16x16x32_bf16 v[52:55], v[192:195], v[208:211], v[52:55]
	v_mfma_f32_16x16x32_bf16 v[52:55], v[196:199], v[212:215], v[52:55]
	v_mfma_f32_16x16x32_bf16 v[44:47], v[200:203], v[208:211], v[44:47]
	v_mfma_f32_16x16x32_bf16 v[44:47], v[204:207], v[212:215], v[44:47]
	v_mfma_f32_16x16x32_bf16 v[36:39], v[192:195], v[216:219], v[36:39]
	v_mfma_f32_16x16x32_bf16 v[36:39], v[196:199], v[222:225], v[36:39]
	v_mfma_f32_16x16x32_bf16 v[26:29], v[200:203], v[216:219], v[26:29]
	v_mfma_f32_16x16x32_bf16 v[26:29], v[204:207], v[222:225], v[26:29]
	v_mfma_f32_16x16x32_bf16 v[18:21], v[192:195], v[226:229], v[18:21]
	v_mfma_f32_16x16x32_bf16 v[18:21], v[196:199], v[230:233], v[18:21]
	v_mfma_f32_16x16x32_bf16 v[10:13], v[200:203], v[226:229], v[10:13]
	v_mfma_f32_16x16x32_bf16 v[10:13], v[204:207], v[230:233], v[10:13]
	v_mfma_f32_16x16x32_bf16 v[6:9], v[192:195], v[234:237], v[6:9]
	v_mfma_f32_16x16x32_bf16 v[6:9], v[196:199], v[238:241], v[6:9]
	v_mfma_f32_16x16x32_bf16 v[2:5], v[200:203], v[234:237], v[2:5]
	v_mfma_f32_16x16x32_bf16 v[2:5], v[204:207], v[238:241], v[2:5]
	s_setprio 0
	s_barrier
	s_add_i32 s26, s26, 2
	s_add_u32 s24, s24, 0x100
	s_addc_u32 s25, s25, 0
	s_add_u32 s62, s62, 0x100
	s_addc_u32 s63, s63, 0
	s_cmp_gt_u32 s26, 29
	s_cbranch_scc0 .LBB0_844
	s_and_b64 vcc, exec, s[44:45]
	s_cbranch_vccz .LBB0_847
	s_barrier

.LBB0_985:
	s_add_u32 s27, s62, 0xfff80080
	s_addc_u32 s28, s63, -1
	s_add_i32 s29, 0, 0x10000
	s_cmp_eq_u32 s26, 28
	s_cselect_b32 s67, s20, s28
	s_cselect_b32 s66, s21, s27
	v_add_u32_e32 v152, s29, v154
	s_cselect_b32 s55, s22, s25
	s_cselect_b32 s54, s23, s24
	s_add_i32 s27, 0, 0x14000
	ds_read_b128 v[158:161], v152
	ds_read_b128 v[180:183], v152 offset:1024
	ds_read_b128 v[184:187], v152 offset:2048
	ds_read_b128 v[188:191], v152 offset:3072
	v_add_u32_e32 v152, s27, v154
	ds_read_b128 v[192:195], v152
	ds_read_b128 v[196:199], v152 offset:1024
	ds_read_b128 v[200:203], v152 offset:2048
	ds_read_b128 v[204:207], v152 offset:3072
	v_lshl_add_u64 v[152:153], s[62:63], 0, v[150:151]
	s_add_i32 m0, s12, 0xc000
	ds_read_b128 v[208:211], v156
	ds_read_b128 v[212:215], v156 offset:1024
	ds_read_b128 v[216:219], v156 offset:2048
	ds_read_b128 v[222:225], v156 offset:3072
	ds_read_b128 v[226:229], v156 offset:4096
	ds_read_b128 v[230:233], v156 offset:5120
	ds_read_b128 v[234:237], v156 offset:6144
	ds_read_b128 v[238:241], v156 offset:7168
	global_load_lds_dwordx4 v[152:153], off
	v_lshl_add_u64 v[152:153], s[62:63], 0, v[148:149]
	s_add_i32 m0, s12, 0xe000
	s_nop 0
	global_load_lds_dwordx4 v[152:153], off
	s_waitcnt vmcnt(8)
	s_waitcnt lgkmcnt(0)
	s_barrier
	s_setprio 1
	s_waitcnt lgkmcnt(0)
	v_mfma_f32_16x16x32_bf16 v[128:131], v[158:161], v[208:211], v[128:131]
	v_mfma_f32_16x16x32_bf16 v[128:131], v[180:183], v[212:215], v[128:131]
	v_mfma_f32_16x16x32_bf16 v[124:127], v[184:187], v[208:211], v[124:127]
	v_mfma_f32_16x16x32_bf16 v[124:127], v[188:191], v[212:215], v[124:127]
	v_mfma_f32_16x16x32_bf16 v[112:115], v[158:161], v[216:219], v[112:115]
	v_mfma_f32_16x16x32_bf16 v[112:115], v[180:183], v[222:225], v[112:115]
	v_mfma_f32_16x16x32_bf16 v[108:111], v[184:187], v[216:219], v[108:111]
	v_mfma_f32_16x16x32_bf16 v[108:111], v[188:191], v[222:225], v[108:111]
	v_mfma_f32_16x16x32_bf16 v[96:99], v[158:161], v[226:229], v[96:99]
	v_mfma_f32_16x16x32_bf16 v[96:99], v[180:183], v[230:233], v[96:99]
	v_mfma_f32_16x16x32_bf16 v[92:95], v[184:187], v[226:229], v[92:95]
	v_mfma_f32_16x16x32_bf16 v[92:95], v[188:191], v[230:233], v[92:95]
	v_mfma_f32_16x16x32_bf16 v[80:83], v[158:161], v[234:237], v[80:83]
	v_mfma_f32_16x16x32_bf16 v[80:83], v[180:183], v[238:241], v[80:83]
	v_mfma_f32_16x16x32_bf16 v[76:79], v[184:187], v[234:237], v[76:79]
	v_mfma_f32_16x16x32_bf16 v[76:79], v[188:191], v[238:241], v[76:79]
	s_setprio 0
	s_setprio 1
	v_mfma_f32_16x16x32_bf16 v[120:123], v[192:195], v[208:211], v[120:123]
	v_mfma_f32_16x16x32_bf16 v[120:123], v[196:199], v[212:215], v[120:123]
	v_mfma_f32_16x16x32_bf16 v[116:119], v[200:203], v[208:211], v[116:119]
	v_mfma_f32_16x16x32_bf16 v[116:119], v[204:207], v[212:215], v[116:119]
	v_mfma_f32_16x16x32_bf16 v[104:107], v[192:195], v[216:219], v[104:107]
	v_mfma_f32_16x16x32_bf16 v[104:107], v[196:199], v[222:225], v[104:107]
	v_mfma_f32_16x16x32_bf16 v[100:103], v[200:203], v[216:219], v[100:103]
	v_mfma_f32_16x16x32_bf16 v[100:103], v[204:207], v[222:225], v[100:103]
	v_mfma_f32_16x16x32_bf16 v[88:91], v[192:195], v[226:229], v[88:91]
	v_mfma_f32_16x16x32_bf16 v[88:91], v[196:199], v[230:233], v[88:91]
	v_mfma_f32_16x16x32_bf16 v[84:87], v[200:203], v[226:229], v[84:87]
	v_mfma_f32_16x16x32_bf16 v[84:87], v[204:207], v[230:233], v[84:87]
	v_mfma_f32_16x16x32_bf16 v[72:75], v[192:195], v[234:237], v[72:75]
	v_mfma_f32_16x16x32_bf16 v[72:75], v[196:199], v[238:241], v[72:75]
	v_mfma_f32_16x16x32_bf16 v[68:71], v[200:203], v[234:237], v[68:71]
	v_mfma_f32_16x16x32_bf16 v[68:71], v[204:207], v[238:241], v[68:71]
	s_setprio 0
	s_barrier
	s_add_i32 s28, s29, s11
	v_lshl_add_u64 v[152:153], s[54:55], 0, v[34:35]
	s_mov_b32 m0, s28
	ds_read_b128 v[208:211], v156 offset:16384
	ds_read_b128 v[212:215], v156 offset:17408
	ds_read_b128 v[216:219], v156 offset:18432
	ds_read_b128 v[222:225], v156 offset:19456
	ds_read_b128 v[226:229], v156 offset:20480
	ds_read_b128 v[230:233], v156 offset:21504
	ds_read_b128 v[234:237], v156 offset:22528
	ds_read_b128 v[238:241], v156 offset:23552
	global_load_lds_dwordx4 v[152:153], off
	s_add_i32 m0, s28, 0x2000
	s_add_u32 s28, s54, 0x80000
	v_lshl_add_u64 v[162:163], s[54:55], 0, v[146:147]
	s_addc_u32 s29, s55, 0
	s_add_i32 s27, s27, s11
	global_load_lds_dwordx4 v[162:163], off
	v_lshl_add_u64 v[242:243], s[28:29], 0, v[34:35]
	s_mov_b32 m0, s27
	v_lshl_add_u64 v[244:245], s[66:67], 0, v[144:145]
	global_load_lds_dwordx4 v[242:243], off
	v_lshl_add_u64 v[242:243], s[28:29], 0, v[146:147]
	s_add_i32 m0, s27, 0x2000
	s_nop 0
	global_load_lds_dwordx4 v[242:243], off
	v_lshl_add_u64 v[242:243], s[66:67], 0, v[142:143]
	s_mov_b32 m0, s12
	s_nop 0
	global_load_lds_dwordx4 v[242:243], off
	s_mov_b32 m0, s13
	s_nop 0
	global_load_lds_dwordx4 v[244:245], off
	s_waitcnt vmcnt(8)
	s_waitcnt lgkmcnt(0)
	s_barrier
	s_setprio 1
	s_waitcnt lgkmcnt(0)
	v_mfma_f32_16x16x32_bf16 v[64:67], v[158:161], v[208:211], v[64:67]
	v_mfma_f32_16x16x32_bf16 v[64:67], v[180:183], v[212:215], v[64:67]
	v_mfma_f32_16x16x32_bf16 v[60:63], v[184:187], v[208:211], v[60:63]
	v_mfma_f32_16x16x32_bf16 v[60:63], v[188:191], v[212:215], v[60:63]
	v_mfma_f32_16x16x32_bf16 v[48:51], v[158:161], v[216:219], v[48:51]
	v_mfma_f32_16x16x32_bf16 v[48:51], v[180:183], v[222:225], v[48:51]
	v_mfma_f32_16x16x32_bf16 v[44:47], v[184:187], v[216:219], v[44:47]
	v_mfma_f32_16x16x32_bf16 v[44:47], v[188:191], v[222:225], v[44:47]
	v_mfma_f32_16x16x32_bf16 v[30:33], v[158:161], v[226:229], v[30:33]
	v_mfma_f32_16x16x32_bf16 v[30:33], v[180:183], v[230:233], v[30:33]
	v_mfma_f32_16x16x32_bf16 v[26:29], v[184:187], v[226:229], v[26:29]
	v_mfma_f32_16x16x32_bf16 v[26:29], v[188:191], v[230:233], v[26:29]
	v_mfma_f32_16x16x32_bf16 v[14:17], v[158:161], v[234:237], v[14:17]
	v_mfma_f32_16x16x32_bf16 v[14:17], v[180:183], v[238:241], v[14:17]
	v_mfma_f32_16x16x32_bf16 v[10:13], v[184:187], v[234:237], v[10:13]
	v_mfma_f32_16x16x32_bf16 v[10:13], v[188:191], v[238:241], v[10:13]
	s_setprio 0
	s_setprio 1
	v_mfma_f32_16x16x32_bf16 v[56:59], v[192:195], v[208:211], v[56:59]
	v_mfma_f32_16x16x32_bf16 v[56:59], v[196:199], v[212:215], v[56:59]
	v_mfma_f32_16x16x32_bf16 v[52:55], v[200:203], v[208:211], v[52:55]
	v_mfma_f32_16x16x32_bf16 v[52:55], v[204:207], v[212:215], v[52:55]
	v_mfma_f32_16x16x32_bf16 v[40:43], v[192:195], v[216:219], v[40:43]
	v_mfma_f32_16x16x32_bf16 v[40:43], v[196:199], v[222:225], v[40:43]
	v_mfma_f32_16x16x32_bf16 v[36:39], v[200:203], v[216:219], v[36:39]
	v_mfma_f32_16x16x32_bf16 v[36:39], v[204:207], v[222:225], v[36:39]
	v_mfma_f32_16x16x32_bf16 v[22:25], v[192:195], v[226:229], v[22:25]
	v_mfma_f32_16x16x32_bf16 v[22:25], v[196:199], v[230:233], v[22:25]
	v_mfma_f32_16x16x32_bf16 v[18:21], v[200:203], v[226:229], v[18:21]
	v_mfma_f32_16x16x32_bf16 v[18:21], v[204:207], v[230:233], v[18:21]
	v_mfma_f32_16x16x32_bf16 v[6:9], v[192:195], v[234:237], v[6:9]
	v_mfma_f32_16x16x32_bf16 v[6:9], v[196:199], v[238:241], v[6:9]
	v_mfma_f32_16x16x32_bf16 v[2:5], v[200:203], v[234:237], v[2:5]
	v_mfma_f32_16x16x32_bf16 v[2:5], v[204:207], v[238:241], v[2:5]
	s_setprio 0
	s_barrier
	s_add_i32 s27, 0, 0x18000
	v_add_u32_e32 v157, s27, v154
	s_add_i32 s30, 0, 0x1c000
	ds_read_b128 v[158:161], v157
	ds_read_b128 v[180:183], v157 offset:1024
	ds_read_b128 v[184:187], v157 offset:2048
	ds_read_b128 v[188:191], v157 offset:3072
	v_add_u32_e32 v157, s30, v154
	ds_read_b128 v[192:195], v157
	ds_read_b128 v[196:199], v157 offset:1024
	ds_read_b128 v[200:203], v157 offset:2048
	ds_read_b128 v[204:207], v157 offset:3072
	s_add_u32 s28, s66, 0x80000
	s_addc_u32 s29, s67, 0
	s_mov_b32 m0, s14
	v_lshl_add_u64 v[246:247], s[28:29], 0, v[142:143]
	ds_read_b128 v[208:211], v156 offset:32768
	ds_read_b128 v[212:215], v156 offset:33792
	ds_read_b128 v[216:219], v156 offset:34816
	ds_read_b128 v[222:225], v156 offset:35840
	ds_read_b128 v[226:229], v156 offset:36864
	ds_read_b128 v[230:233], v156 offset:37888
	ds_read_b128 v[234:237], v156 offset:38912
	ds_read_b128 v[238:241], v156 offset:39936
	global_load_lds_dwordx4 v[246:247], off
	v_lshl_add_u64 v[246:247], s[28:29], 0, v[144:145]
	s_mov_b32 m0, s15
	s_nop 0
	global_load_lds_dwordx4 v[246:247], off
	s_waitcnt vmcnt(8)
	s_waitcnt lgkmcnt(0)
	s_barrier
	s_setprio 1
	s_waitcnt lgkmcnt(0)
	v_mfma_f32_16x16x32_bf16 v[128:131], v[158:161], v[208:211], v[128:131]
	v_mfma_f32_16x16x32_bf16 v[128:131], v[180:183], v[212:215], v[128:131]
	v_mfma_f32_16x16x32_bf16 v[124:127], v[184:187], v[208:211], v[124:127]
	v_mfma_f32_16x16x32_bf16 v[124:127], v[188:191], v[212:215], v[124:127]
	v_mfma_f32_16x16x32_bf16 v[112:115], v[158:161], v[216:219], v[112:115]
	v_mfma_f32_16x16x32_bf16 v[112:115], v[180:183], v[222:225], v[112:115]
	v_mfma_f32_16x16x32_bf16 v[108:111], v[184:187], v[216:219], v[108:111]
	v_mfma_f32_16x16x32_bf16 v[108:111], v[188:191], v[222:225], v[108:111]
	v_mfma_f32_16x16x32_bf16 v[96:99], v[158:161], v[226:229], v[96:99]
	v_mfma_f32_16x16x32_bf16 v[96:99], v[180:183], v[230:233], v[96:99]
	v_mfma_f32_16x16x32_bf16 v[92:95], v[184:187], v[226:229], v[92:95]
	v_mfma_f32_16x16x32_bf16 v[92:95], v[188:191], v[230:233], v[92:95]
	v_mfma_f32_16x16x32_bf16 v[80:83], v[158:161], v[234:237], v[80:83]
	v_mfma_f32_16x16x32_bf16 v[80:83], v[180:183], v[238:241], v[80:83]
	v_mfma_f32_16x16x32_bf16 v[76:79], v[184:187], v[234:237], v[76:79]
	v_mfma_f32_16x16x32_bf16 v[76:79], v[188:191], v[238:241], v[76:79]
	s_setprio 0
	s_setprio 1
	v_mfma_f32_16x16x32_bf16 v[120:123], v[192:195], v[208:211], v[120:123]
	v_mfma_f32_16x16x32_bf16 v[120:123], v[196:199], v[212:215], v[120:123]
	v_mfma_f32_16x16x32_bf16 v[116:119], v[200:203], v[208:211], v[116:119]
	v_mfma_f32_16x16x32_bf16 v[116:119], v[204:207], v[212:215], v[116:119]
	v_mfma_f32_16x16x32_bf16 v[104:107], v[192:195], v[216:219], v[104:107]
	v_mfma_f32_16x16x32_bf16 v[104:107], v[196:199], v[222:225], v[104:107]
	v_mfma_f32_16x16x32_bf16 v[100:103], v[200:203], v[216:219], v[100:103]
	v_mfma_f32_16x16x32_bf16 v[100:103], v[204:207], v[222:225], v[100:103]
	v_mfma_f32_16x16x32_bf16 v[88:91], v[192:195], v[226:229], v[88:91]
	v_mfma_f32_16x16x32_bf16 v[88:91], v[196:199], v[230:233], v[88:91]
	v_mfma_f32_16x16x32_bf16 v[84:87], v[200:203], v[226:229], v[84:87]
	v_mfma_f32_16x16x32_bf16 v[84:87], v[204:207], v[230:233], v[84:87]
	v_mfma_f32_16x16x32_bf16 v[72:75], v[192:195], v[234:237], v[72:75]
	v_mfma_f32_16x16x32_bf16 v[72:75], v[196:199], v[238:241], v[72:75]
	v_mfma_f32_16x16x32_bf16 v[68:71], v[200:203], v[234:237], v[68:71]
	v_mfma_f32_16x16x32_bf16 v[68:71], v[204:207], v[238:241], v[68:71]
	s_setprio 0
	s_barrier
	s_add_i32 s27, s27, s11
	v_lshl_add_u64 v[152:153], v[152:153], 0, s[78:79]
	s_mov_b32 m0, s27
	ds_read_b128 v[208:211], v156 offset:49152
	ds_read_b128 v[212:215], v156 offset:50176
	ds_read_b128 v[216:219], v156 offset:51200
	ds_read_b128 v[222:225], v156 offset:52224
	ds_read_b128 v[226:229], v156 offset:53248
	ds_read_b128 v[230:233], v156 offset:54272
	ds_read_b128 v[234:237], v156 offset:55296
	ds_read_b128 v[238:241], v156 offset:56320
	global_load_lds_dwordx4 v[152:153], off
	s_add_i32 m0, s27, 0x2000
	s_add_u32 s28, s54, 0x80080
	v_lshl_add_u64 v[152:153], v[162:163], 0, s[78:79]
	s_addc_u32 s29, s55, 0
	s_add_i32 s27, s30, s11
	global_load_lds_dwordx4 v[152:153], off
	v_lshl_add_u64 v[152:153], s[28:29], 0, v[34:35]
	s_mov_b32 m0, s27
	s_nop 0
	global_load_lds_dwordx4 v[152:153], off
	v_lshl_add_u64 v[152:153], s[28:29], 0, v[146:147]
	s_add_i32 m0, s27, 0x2000
	s_nop 0
	global_load_lds_dwordx4 v[152:153], off
	v_lshl_add_u64 v[152:153], v[242:243], 0, s[78:79]
	s_mov_b32 m0, s16
	s_nop 0
	global_load_lds_dwordx4 v[152:153], off
	v_lshl_add_u64 v[152:153], v[244:245], 0, s[78:79]
	s_mov_b32 m0, s17
	s_nop 0
	global_load_lds_dwordx4 v[152:153], off
	s_waitcnt vmcnt(8)
	s_waitcnt lgkmcnt(0)
	s_barrier
	s_setprio 1
	s_waitcnt lgkmcnt(0)
	v_mfma_f32_16x16x32_bf16 v[64:67], v[158:161], v[208:211], v[64:67]
	v_mfma_f32_16x16x32_bf16 v[64:67], v[180:183], v[212:215], v[64:67]
	v_mfma_f32_16x16x32_bf16 v[60:63], v[184:187], v[208:211], v[60:63]
	v_mfma_f32_16x16x32_bf16 v[60:63], v[188:191], v[212:215], v[60:63]
	v_mfma_f32_16x16x32_bf16 v[48:51], v[158:161], v[216:219], v[48:51]
	v_mfma_f32_16x16x32_bf16 v[48:51], v[180:183], v[222:225], v[48:51]
	v_mfma_f32_16x16x32_bf16 v[44:47], v[184:187], v[216:219], v[44:47]
	v_mfma_f32_16x16x32_bf16 v[44:47], v[188:191], v[222:225], v[44:47]
	v_mfma_f32_16x16x32_bf16 v[30:33], v[158:161], v[226:229], v[30:33]
	v_mfma_f32_16x16x32_bf16 v[30:33], v[180:183], v[230:233], v[30:33]
	v_mfma_f32_16x16x32_bf16 v[26:29], v[184:187], v[226:229], v[26:29]
	v_mfma_f32_16x16x32_bf16 v[26:29], v[188:191], v[230:233], v[26:29]
	v_mfma_f32_16x16x32_bf16 v[14:17], v[158:161], v[234:237], v[14:17]
	v_mfma_f32_16x16x32_bf16 v[14:17], v[180:183], v[238:241], v[14:17]
	v_mfma_f32_16x16x32_bf16 v[10:13], v[184:187], v[234:237], v[10:13]
	v_mfma_f32_16x16x32_bf16 v[10:13], v[188:191], v[238:241], v[10:13]
	s_setprio 0
	s_setprio 1
	v_mfma_f32_16x16x32_bf16 v[56:59], v[192:195], v[208:211], v[56:59]
	v_mfma_f32_16x16x32_bf16 v[56:59], v[196:199], v[212:215], v[56:59]
	v_mfma_f32_16x16x32_bf16 v[52:55], v[200:203], v[208:211], v[52:55]
	v_mfma_f32_16x16x32_bf16 v[52:55], v[204:207], v[212:215], v[52:55]
	v_mfma_f32_16x16x32_bf16 v[40:43], v[192:195], v[216:219], v[40:43]
	v_mfma_f32_16x16x32_bf16 v[40:43], v[196:199], v[222:225], v[40:43]
	v_mfma_f32_16x16x32_bf16 v[36:39], v[200:203], v[216:219], v[36:39]
	v_mfma_f32_16x16x32_bf16 v[36:39], v[204:207], v[222:225], v[36:39]
	v_mfma_f32_16x16x32_bf16 v[22:25], v[192:195], v[226:229], v[22:25]
	v_mfma_f32_16x16x32_bf16 v[22:25], v[196:199], v[230:233], v[22:25]
	v_mfma_f32_16x16x32_bf16 v[18:21], v[200:203], v[226:229], v[18:21]
	v_mfma_f32_16x16x32_bf16 v[18:21], v[204:207], v[230:233], v[18:21]
	v_mfma_f32_16x16x32_bf16 v[6:9], v[192:195], v[234:237], v[6:9]
	v_mfma_f32_16x16x32_bf16 v[6:9], v[196:199], v[238:241], v[6:9]
	v_mfma_f32_16x16x32_bf16 v[2:5], v[200:203], v[234:237], v[2:5]
	v_mfma_f32_16x16x32_bf16 v[2:5], v[204:207], v[238:241], v[2:5]
	s_setprio 0
	s_barrier
	s_add_i32 s26, s26, 2
	s_add_u32 s24, s24, 0x100
	s_addc_u32 s25, s25, 0
	s_add_u32 s62, s62, 0x100
	s_addc_u32 s63, s63, 0
	s_cmp_gt_u32 s26, 29
	s_cbranch_scc0 .LBB0_985
	s_and_b64 vcc, exec, s[36:37]
	s_cbranch_vccz .LBB0_988
	s_barrier

.LBB0_1064:
	s_add_u32 s27, s62, 0xffe00080
	s_addc_u32 s28, s63, -1
	s_add_i32 s29, 0, 0x10000
	s_cmpk_eq_i32 s26, 0x7c
	s_cselect_b32 s67, s20, s28
	s_cselect_b32 s66, s21, s27
	v_add_u32_e32 v152, s29, v154
	s_cselect_b32 s55, s22, s25
	s_cselect_b32 s54, s23, s24
	s_add_i32 s27, 0, 0x14000
	ds_read_b128 v[158:161], v152
	ds_read_b128 v[180:183], v152 offset:1024
	ds_read_b128 v[184:187], v152 offset:2048
	ds_read_b128 v[188:191], v152 offset:3072
	v_add_u32_e32 v152, s27, v154
	ds_read_b128 v[192:195], v152
	ds_read_b128 v[196:199], v152 offset:1024
	ds_read_b128 v[200:203], v152 offset:2048
	ds_read_b128 v[204:207], v152 offset:3072
	v_lshl_add_u64 v[152:153], s[62:63], 0, v[150:151]
	s_add_i32 m0, s12, 0xc000
	ds_read_b128 v[208:211], v156
	ds_read_b128 v[212:215], v156 offset:1024
	ds_read_b128 v[216:219], v156 offset:2048
	ds_read_b128 v[222:225], v156 offset:3072
	ds_read_b128 v[226:229], v156 offset:4096
	ds_read_b128 v[230:233], v156 offset:5120
	ds_read_b128 v[234:237], v156 offset:6144
	ds_read_b128 v[238:241], v156 offset:7168
	global_load_lds_dwordx4 v[152:153], off
	v_lshl_add_u64 v[152:153], s[62:63], 0, v[148:149]
	s_add_i32 m0, s12, 0xe000
	s_nop 0
	global_load_lds_dwordx4 v[152:153], off
	s_waitcnt vmcnt(8)
	s_waitcnt lgkmcnt(0)
	s_barrier
	s_setprio 1
	s_waitcnt lgkmcnt(0)
	v_mfma_f32_16x16x32_bf16 v[128:131], v[158:161], v[208:211], v[128:131]
	v_mfma_f32_16x16x32_bf16 v[128:131], v[180:183], v[212:215], v[128:131]
	v_mfma_f32_16x16x32_bf16 v[124:127], v[184:187], v[208:211], v[124:127]
	v_mfma_f32_16x16x32_bf16 v[124:127], v[188:191], v[212:215], v[124:127]
	v_mfma_f32_16x16x32_bf16 v[120:123], v[158:161], v[216:219], v[120:123]
	v_mfma_f32_16x16x32_bf16 v[120:123], v[180:183], v[222:225], v[120:123]
	v_mfma_f32_16x16x32_bf16 v[112:115], v[184:187], v[216:219], v[112:115]
	v_mfma_f32_16x16x32_bf16 v[112:115], v[188:191], v[222:225], v[112:115]
	v_mfma_f32_16x16x32_bf16 v[104:107], v[158:161], v[226:229], v[104:107]
	v_mfma_f32_16x16x32_bf16 v[104:107], v[180:183], v[230:233], v[104:107]
	v_mfma_f32_16x16x32_bf16 v[96:99], v[184:187], v[226:229], v[96:99]
	v_mfma_f32_16x16x32_bf16 v[96:99], v[188:191], v[230:233], v[96:99]
	v_mfma_f32_16x16x32_bf16 v[88:91], v[158:161], v[234:237], v[88:91]
	v_mfma_f32_16x16x32_bf16 v[88:91], v[180:183], v[238:241], v[88:91]
	v_mfma_f32_16x16x32_bf16 v[80:83], v[184:187], v[234:237], v[80:83]
	v_mfma_f32_16x16x32_bf16 v[80:83], v[188:191], v[238:241], v[80:83]
	s_setprio 0
	s_setprio 1
	v_mfma_f32_16x16x32_bf16 v[116:119], v[192:195], v[208:211], v[116:119]
	v_mfma_f32_16x16x32_bf16 v[116:119], v[196:199], v[212:215], v[116:119]
	v_mfma_f32_16x16x32_bf16 v[108:111], v[200:203], v[208:211], v[108:111]
	v_mfma_f32_16x16x32_bf16 v[108:111], v[204:207], v[212:215], v[108:111]
	v_mfma_f32_16x16x32_bf16 v[100:103], v[192:195], v[216:219], v[100:103]
	v_mfma_f32_16x16x32_bf16 v[100:103], v[196:199], v[222:225], v[100:103]
	v_mfma_f32_16x16x32_bf16 v[92:95], v[200:203], v[216:219], v[92:95]
	v_mfma_f32_16x16x32_bf16 v[92:95], v[204:207], v[222:225], v[92:95]
	v_mfma_f32_16x16x32_bf16 v[84:87], v[192:195], v[226:229], v[84:87]
	v_mfma_f32_16x16x32_bf16 v[84:87], v[196:199], v[230:233], v[84:87]
	v_mfma_f32_16x16x32_bf16 v[76:79], v[200:203], v[226:229], v[76:79]
	v_mfma_f32_16x16x32_bf16 v[76:79], v[204:207], v[230:233], v[76:79]
	v_mfma_f32_16x16x32_bf16 v[72:75], v[192:195], v[234:237], v[72:75]
	v_mfma_f32_16x16x32_bf16 v[72:75], v[196:199], v[238:241], v[72:75]
	v_mfma_f32_16x16x32_bf16 v[68:71], v[200:203], v[234:237], v[68:71]
	v_mfma_f32_16x16x32_bf16 v[68:71], v[204:207], v[238:241], v[68:71]
	s_setprio 0
	s_barrier
	s_add_i32 s28, s29, s11
	v_lshl_add_u64 v[152:153], s[54:55], 0, v[34:35]
	s_mov_b32 m0, s28
	ds_read_b128 v[208:211], v156 offset:16384
	ds_read_b128 v[212:215], v156 offset:17408
	ds_read_b128 v[216:219], v156 offset:18432
	ds_read_b128 v[222:225], v156 offset:19456
	ds_read_b128 v[226:229], v156 offset:20480
	ds_read_b128 v[230:233], v156 offset:21504
	ds_read_b128 v[234:237], v156 offset:22528
	ds_read_b128 v[238:241], v156 offset:23552
	global_load_lds_dwordx4 v[152:153], off
	s_add_i32 m0, s28, 0x2000
	s_add_u32 s28, s54, 0x200000
	v_lshl_add_u64 v[162:163], s[54:55], 0, v[146:147]
	s_addc_u32 s29, s55, 0
	s_add_i32 s27, s27, s11
	global_load_lds_dwordx4 v[162:163], off
	v_lshl_add_u64 v[242:243], s[28:29], 0, v[34:35]
	s_mov_b32 m0, s27
	v_lshl_add_u64 v[244:245], s[66:67], 0, v[144:145]
	global_load_lds_dwordx4 v[242:243], off
	v_lshl_add_u64 v[242:243], s[28:29], 0, v[146:147]
	s_add_i32 m0, s27, 0x2000
	s_nop 0
	global_load_lds_dwordx4 v[242:243], off
	v_lshl_add_u64 v[242:243], s[66:67], 0, v[142:143]
	s_mov_b32 m0, s12
	s_nop 0
	global_load_lds_dwordx4 v[242:243], off
	s_mov_b32 m0, s13
	s_nop 0
	global_load_lds_dwordx4 v[244:245], off
	s_waitcnt vmcnt(8)
	s_waitcnt lgkmcnt(0)
	s_barrier
	s_setprio 1
	s_waitcnt lgkmcnt(0)
	v_mfma_f32_16x16x32_bf16 v[64:67], v[158:161], v[208:211], v[64:67]
	v_mfma_f32_16x16x32_bf16 v[64:67], v[180:183], v[212:215], v[64:67]
	v_mfma_f32_16x16x32_bf16 v[60:63], v[184:187], v[208:211], v[60:63]
	v_mfma_f32_16x16x32_bf16 v[60:63], v[188:191], v[212:215], v[60:63]
	v_mfma_f32_16x16x32_bf16 v[56:59], v[158:161], v[216:219], v[56:59]
	v_mfma_f32_16x16x32_bf16 v[56:59], v[180:183], v[222:225], v[56:59]
	v_mfma_f32_16x16x32_bf16 v[48:51], v[184:187], v[216:219], v[48:51]
	v_mfma_f32_16x16x32_bf16 v[48:51], v[188:191], v[222:225], v[48:51]
	v_mfma_f32_16x16x32_bf16 v[40:43], v[158:161], v[226:229], v[40:43]
	v_mfma_f32_16x16x32_bf16 v[40:43], v[180:183], v[230:233], v[40:43]
	v_mfma_f32_16x16x32_bf16 v[30:33], v[184:187], v[226:229], v[30:33]
	v_mfma_f32_16x16x32_bf16 v[30:33], v[188:191], v[230:233], v[30:33]
	v_mfma_f32_16x16x32_bf16 v[22:25], v[158:161], v[234:237], v[22:25]
	v_mfma_f32_16x16x32_bf16 v[22:25], v[180:183], v[238:241], v[22:25]
	v_mfma_f32_16x16x32_bf16 v[14:17], v[184:187], v[234:237], v[14:17]
	v_mfma_f32_16x16x32_bf16 v[14:17], v[188:191], v[238:241], v[14:17]
	s_setprio 0
	s_setprio 1
	v_mfma_f32_16x16x32_bf16 v[52:55], v[192:195], v[208:211], v[52:55]
	v_mfma_f32_16x16x32_bf16 v[52:55], v[196:199], v[212:215], v[52:55]
	v_mfma_f32_16x16x32_bf16 v[44:47], v[200:203], v[208:211], v[44:47]
	v_mfma_f32_16x16x32_bf16 v[44:47], v[204:207], v[212:215], v[44:47]
	v_mfma_f32_16x16x32_bf16 v[36:39], v[192:195], v[216:219], v[36:39]
	v_mfma_f32_16x16x32_bf16 v[36:39], v[196:199], v[222:225], v[36:39]
	v_mfma_f32_16x16x32_bf16 v[26:29], v[200:203], v[216:219], v[26:29]
	v_mfma_f32_16x16x32_bf16 v[26:29], v[204:207], v[222:225], v[26:29]
	v_mfma_f32_16x16x32_bf16 v[18:21], v[192:195], v[226:229], v[18:21]
	v_mfma_f32_16x16x32_bf16 v[18:21], v[196:199], v[230:233], v[18:21]
	v_mfma_f32_16x16x32_bf16 v[10:13], v[200:203], v[226:229], v[10:13]
	v_mfma_f32_16x16x32_bf16 v[10:13], v[204:207], v[230:233], v[10:13]
	v_mfma_f32_16x16x32_bf16 v[6:9], v[192:195], v[234:237], v[6:9]
	v_mfma_f32_16x16x32_bf16 v[6:9], v[196:199], v[238:241], v[6:9]
	v_mfma_f32_16x16x32_bf16 v[2:5], v[200:203], v[234:237], v[2:5]
	v_mfma_f32_16x16x32_bf16 v[2:5], v[204:207], v[238:241], v[2:5]
	s_setprio 0
	s_barrier
	s_add_i32 s27, 0, 0x18000
	v_add_u32_e32 v157, s27, v154
	s_add_i32 s30, 0, 0x1c000
	ds_read_b128 v[158:161], v157
	ds_read_b128 v[180:183], v157 offset:1024
	ds_read_b128 v[184:187], v157 offset:2048
	ds_read_b128 v[188:191], v157 offset:3072
	v_add_u32_e32 v157, s30, v154
	ds_read_b128 v[192:195], v157
	ds_read_b128 v[196:199], v157 offset:1024
	ds_read_b128 v[200:203], v157 offset:2048
	ds_read_b128 v[204:207], v157 offset:3072
	s_add_u32 s28, s66, 0x200000
	s_addc_u32 s29, s67, 0
	s_mov_b32 m0, s14
	v_lshl_add_u64 v[246:247], s[28:29], 0, v[142:143]
	ds_read_b128 v[208:211], v156 offset:32768
	ds_read_b128 v[212:215], v156 offset:33792
	ds_read_b128 v[216:219], v156 offset:34816
	ds_read_b128 v[222:225], v156 offset:35840
	ds_read_b128 v[226:229], v156 offset:36864
	ds_read_b128 v[230:233], v156 offset:37888
	ds_read_b128 v[234:237], v156 offset:38912
	ds_read_b128 v[238:241], v156 offset:39936
	global_load_lds_dwordx4 v[246:247], off
	v_lshl_add_u64 v[246:247], s[28:29], 0, v[144:145]
	s_mov_b32 m0, s15
	s_nop 0
	global_load_lds_dwordx4 v[246:247], off
	s_waitcnt vmcnt(8)
	s_waitcnt lgkmcnt(0)
	s_barrier
	s_setprio 1
	s_waitcnt lgkmcnt(0)
	v_mfma_f32_16x16x32_bf16 v[128:131], v[158:161], v[208:211], v[128:131]
	v_mfma_f32_16x16x32_bf16 v[128:131], v[180:183], v[212:215], v[128:131]
	v_mfma_f32_16x16x32_bf16 v[124:127], v[184:187], v[208:211], v[124:127]
	v_mfma_f32_16x16x32_bf16 v[124:127], v[188:191], v[212:215], v[124:127]
	v_mfma_f32_16x16x32_bf16 v[120:123], v[158:161], v[216:219], v[120:123]
	v_mfma_f32_16x16x32_bf16 v[120:123], v[180:183], v[222:225], v[120:123]
	v_mfma_f32_16x16x32_bf16 v[112:115], v[184:187], v[216:219], v[112:115]
	v_mfma_f32_16x16x32_bf16 v[112:115], v[188:191], v[222:225], v[112:115]
	v_mfma_f32_16x16x32_bf16 v[104:107], v[158:161], v[226:229], v[104:107]
	v_mfma_f32_16x16x32_bf16 v[104:107], v[180:183], v[230:233], v[104:107]
	v_mfma_f32_16x16x32_bf16 v[96:99], v[184:187], v[226:229], v[96:99]
	v_mfma_f32_16x16x32_bf16 v[96:99], v[188:191], v[230:233], v[96:99]
	v_mfma_f32_16x16x32_bf16 v[88:91], v[158:161], v[234:237], v[88:91]
	v_mfma_f32_16x16x32_bf16 v[88:91], v[180:183], v[238:241], v[88:91]
	v_mfma_f32_16x16x32_bf16 v[80:83], v[184:187], v[234:237], v[80:83]
	v_mfma_f32_16x16x32_bf16 v[80:83], v[188:191], v[238:241], v[80:83]
	s_setprio 0
	s_setprio 1
	v_mfma_f32_16x16x32_bf16 v[116:119], v[192:195], v[208:211], v[116:119]
	v_mfma_f32_16x16x32_bf16 v[116:119], v[196:199], v[212:215], v[116:119]
	v_mfma_f32_16x16x32_bf16 v[108:111], v[200:203], v[208:211], v[108:111]
	v_mfma_f32_16x16x32_bf16 v[108:111], v[204:207], v[212:215], v[108:111]
	v_mfma_f32_16x16x32_bf16 v[100:103], v[192:195], v[216:219], v[100:103]
	v_mfma_f32_16x16x32_bf16 v[100:103], v[196:199], v[222:225], v[100:103]
	v_mfma_f32_16x16x32_bf16 v[92:95], v[200:203], v[216:219], v[92:95]
	v_mfma_f32_16x16x32_bf16 v[92:95], v[204:207], v[222:225], v[92:95]
	v_mfma_f32_16x16x32_bf16 v[84:87], v[192:195], v[226:229], v[84:87]
	v_mfma_f32_16x16x32_bf16 v[84:87], v[196:199], v[230:233], v[84:87]
	v_mfma_f32_16x16x32_bf16 v[76:79], v[200:203], v[226:229], v[76:79]
	v_mfma_f32_16x16x32_bf16 v[76:79], v[204:207], v[230:233], v[76:79]
	v_mfma_f32_16x16x32_bf16 v[72:75], v[192:195], v[234:237], v[72:75]
	v_mfma_f32_16x16x32_bf16 v[72:75], v[196:199], v[238:241], v[72:75]
	v_mfma_f32_16x16x32_bf16 v[68:71], v[200:203], v[234:237], v[68:71]
	v_mfma_f32_16x16x32_bf16 v[68:71], v[204:207], v[238:241], v[68:71]
	s_setprio 0
	s_barrier
	s_add_i32 s27, s27, s11
	v_lshl_add_u64 v[152:153], v[152:153], 0, s[78:79]
	s_mov_b32 m0, s27
	ds_read_b128 v[208:211], v156 offset:49152
	ds_read_b128 v[212:215], v156 offset:50176
	ds_read_b128 v[216:219], v156 offset:51200
	ds_read_b128 v[222:225], v156 offset:52224
	ds_read_b128 v[226:229], v156 offset:53248
	ds_read_b128 v[230:233], v156 offset:54272
	ds_read_b128 v[234:237], v156 offset:55296
	ds_read_b128 v[238:241], v156 offset:56320
	global_load_lds_dwordx4 v[152:153], off
	s_add_i32 m0, s27, 0x2000
	s_add_u32 s28, s54, 0x200080
	v_lshl_add_u64 v[152:153], v[162:163], 0, s[78:79]
	s_addc_u32 s29, s55, 0
	s_add_i32 s27, s30, s11
	global_load_lds_dwordx4 v[152:153], off
	v_lshl_add_u64 v[152:153], s[28:29], 0, v[34:35]
	s_mov_b32 m0, s27
	s_nop 0
	global_load_lds_dwordx4 v[152:153], off
	v_lshl_add_u64 v[152:153], s[28:29], 0, v[146:147]
	s_add_i32 m0, s27, 0x2000
	s_nop 0
	global_load_lds_dwordx4 v[152:153], off
	v_lshl_add_u64 v[152:153], v[242:243], 0, s[78:79]
	s_mov_b32 m0, s16
	s_nop 0
	global_load_lds_dwordx4 v[152:153], off
	v_lshl_add_u64 v[152:153], v[244:245], 0, s[78:79]
	s_mov_b32 m0, s17
	s_nop 0
	global_load_lds_dwordx4 v[152:153], off
	s_waitcnt vmcnt(8)
	s_waitcnt lgkmcnt(0)
	s_barrier
	s_setprio 1
	s_waitcnt lgkmcnt(0)
	v_mfma_f32_16x16x32_bf16 v[64:67], v[158:161], v[208:211], v[64:67]
	v_mfma_f32_16x16x32_bf16 v[64:67], v[180:183], v[212:215], v[64:67]
	v_mfma_f32_16x16x32_bf16 v[60:63], v[184:187], v[208:211], v[60:63]
	v_mfma_f32_16x16x32_bf16 v[60:63], v[188:191], v[212:215], v[60:63]
	v_mfma_f32_16x16x32_bf16 v[56:59], v[158:161], v[216:219], v[56:59]
	v_mfma_f32_16x16x32_bf16 v[56:59], v[180:183], v[222:225], v[56:59]
	v_mfma_f32_16x16x32_bf16 v[48:51], v[184:187], v[216:219], v[48:51]
	v_mfma_f32_16x16x32_bf16 v[48:51], v[188:191], v[222:225], v[48:51]
	v_mfma_f32_16x16x32_bf16 v[40:43], v[158:161], v[226:229], v[40:43]
	v_mfma_f32_16x16x32_bf16 v[40:43], v[180:183], v[230:233], v[40:43]
	v_mfma_f32_16x16x32_bf16 v[30:33], v[184:187], v[226:229], v[30:33]
	v_mfma_f32_16x16x32_bf16 v[30:33], v[188:191], v[230:233], v[30:33]
	v_mfma_f32_16x16x32_bf16 v[22:25], v[158:161], v[234:237], v[22:25]
	v_mfma_f32_16x16x32_bf16 v[22:25], v[180:183], v[238:241], v[22:25]
	v_mfma_f32_16x16x32_bf16 v[14:17], v[184:187], v[234:237], v[14:17]
	v_mfma_f32_16x16x32_bf16 v[14:17], v[188:191], v[238:241], v[14:17]
	s_setprio 0
	s_setprio 1
	v_mfma_f32_16x16x32_bf16 v[52:55], v[192:195], v[208:211], v[52:55]
	v_mfma_f32_16x16x32_bf16 v[52:55], v[196:199], v[212:215], v[52:55]
	v_mfma_f32_16x16x32_bf16 v[44:47], v[200:203], v[208:211], v[44:47]
	v_mfma_f32_16x16x32_bf16 v[44:47], v[204:207], v[212:215], v[44:47]
	v_mfma_f32_16x16x32_bf16 v[36:39], v[192:195], v[216:219], v[36:39]
	v_mfma_f32_16x16x32_bf16 v[36:39], v[196:199], v[222:225], v[36:39]
	v_mfma_f32_16x16x32_bf16 v[26:29], v[200:203], v[216:219], v[26:29]
	v_mfma_f32_16x16x32_bf16 v[26:29], v[204:207], v[222:225], v[26:29]
	v_mfma_f32_16x16x32_bf16 v[18:21], v[192:195], v[226:229], v[18:21]
	v_mfma_f32_16x16x32_bf16 v[18:21], v[196:199], v[230:233], v[18:21]
	v_mfma_f32_16x16x32_bf16 v[10:13], v[200:203], v[226:229], v[10:13]
	v_mfma_f32_16x16x32_bf16 v[10:13], v[204:207], v[230:233], v[10:13]
	v_mfma_f32_16x16x32_bf16 v[6:9], v[192:195], v[234:237], v[6:9]
	v_mfma_f32_16x16x32_bf16 v[6:9], v[196:199], v[238:241], v[6:9]
	v_mfma_f32_16x16x32_bf16 v[2:5], v[200:203], v[234:237], v[2:5]
	v_mfma_f32_16x16x32_bf16 v[2:5], v[204:207], v[238:241], v[2:5]
	s_setprio 0
	s_barrier
	s_add_i32 s26, s26, 2
	s_add_u32 s24, s24, 0x100
	s_addc_u32 s25, s25, 0
	s_add_u32 s62, s62, 0x100
	s_addc_u32 s63, s63, 0
	s_cmpk_gt_u32 s26, 0x7d
	s_cbranch_scc0 .LBB0_1064
	s_and_b64 vcc, exec, s[44:45]
	s_cbranch_vccz .LBB0_1067
	s_barrier

.LBB0_1207:
	s_add_u32 s30, s90, 0xfff80080
	s_addc_u32 s31, s91, -1
	s_add_i32 s40, 0, 0x10000
	s_cmp_eq_u32 s29, 28
	s_cselect_b32 vcc_hi, s23, s31
	s_cselect_b32 vcc_lo, s24, s30
	v_add_u32_e32 v142, s40, v146
	s_cselect_b32 s55, s25, s28
	s_cselect_b32 s54, s26, s27
	s_add_i32 s44, 0, 0x14000
	ds_read_b128 v[150:153], v142
	ds_read_b128 v[154:157], v142 offset:1024
	ds_read_b128 v[158:161], v142 offset:2048
	ds_read_b128 v[162:165], v142 offset:3072
	v_add_u32_e32 v142, s44, v146
	ds_read_b128 v[166:169], v142
	ds_read_b128 v[170:173], v142 offset:1024
	ds_read_b128 v[174:177], v142 offset:2048
	ds_read_b128 v[178:181], v142 offset:3072
	v_lshl_add_u64 v[144:145], s[90:91], 0, v[138:139]
	s_add_i32 m0, s15, 0xc000
	ds_read_b128 v[182:185], v148
	ds_read_b128 v[186:189], v148 offset:1024
	ds_read_b128 v[190:193], v148 offset:2048
	ds_read_b128 v[210:213], v148 offset:3072
	ds_read_b128 v[214:217], v148 offset:4096
	ds_read_b128 v[230:233], v148 offset:5120
	ds_read_b128 v[234:237], v148 offset:6144
	ds_read_b128 v[238:241], v148 offset:7168
	global_load_lds_dwordx4 v[144:145], off
	v_lshl_add_u64 v[144:145], s[90:91], 0, v[136:137]
	s_add_i32 m0, s15, 0xe000
	s_nop 0
	global_load_lds_dwordx4 v[144:145], off
	s_waitcnt vmcnt(8)
	s_waitcnt lgkmcnt(0)
	s_barrier
	s_setprio 1
	s_waitcnt lgkmcnt(0)
	v_mfma_f32_16x16x32_bf16 v[126:129], v[150:153], v[182:185], v[126:129]
	v_mfma_f32_16x16x32_bf16 v[126:129], v[154:157], v[186:189], v[126:129]
	v_mfma_f32_16x16x32_bf16 v[122:125], v[158:161], v[182:185], v[122:125]
	v_mfma_f32_16x16x32_bf16 v[122:125], v[162:165], v[186:189], v[122:125]
	v_mfma_f32_16x16x32_bf16 v[114:117], v[150:153], v[190:193], v[114:117]
	v_mfma_f32_16x16x32_bf16 v[114:117], v[154:157], v[210:213], v[114:117]
	v_mfma_f32_16x16x32_bf16 v[106:109], v[158:161], v[190:193], v[106:109]
	v_mfma_f32_16x16x32_bf16 v[106:109], v[162:165], v[210:213], v[106:109]
	v_mfma_f32_16x16x32_bf16 v[98:101], v[150:153], v[214:217], v[98:101]
	v_mfma_f32_16x16x32_bf16 v[98:101], v[154:157], v[230:233], v[98:101]
	v_mfma_f32_16x16x32_bf16 v[90:93], v[158:161], v[214:217], v[90:93]
	v_mfma_f32_16x16x32_bf16 v[90:93], v[162:165], v[230:233], v[90:93]
	v_mfma_f32_16x16x32_bf16 v[82:85], v[150:153], v[234:237], v[82:85]
	v_mfma_f32_16x16x32_bf16 v[82:85], v[154:157], v[238:241], v[82:85]
	v_mfma_f32_16x16x32_bf16 v[74:77], v[158:161], v[234:237], v[74:77]
	v_mfma_f32_16x16x32_bf16 v[74:77], v[162:165], v[238:241], v[74:77]
	s_setprio 0
	s_setprio 1
	v_mfma_f32_16x16x32_bf16 v[118:121], v[166:169], v[182:185], v[118:121]
	v_mfma_f32_16x16x32_bf16 v[118:121], v[170:173], v[186:189], v[118:121]
	v_mfma_f32_16x16x32_bf16 v[110:113], v[174:177], v[182:185], v[110:113]
	v_mfma_f32_16x16x32_bf16 v[110:113], v[178:181], v[186:189], v[110:113]
	v_mfma_f32_16x16x32_bf16 v[102:105], v[166:169], v[190:193], v[102:105]
	v_mfma_f32_16x16x32_bf16 v[102:105], v[170:173], v[210:213], v[102:105]
	v_mfma_f32_16x16x32_bf16 v[94:97], v[174:177], v[190:193], v[94:97]
	v_mfma_f32_16x16x32_bf16 v[94:97], v[178:181], v[210:213], v[94:97]
	v_mfma_f32_16x16x32_bf16 v[86:89], v[166:169], v[214:217], v[86:89]
	v_mfma_f32_16x16x32_bf16 v[86:89], v[170:173], v[230:233], v[86:89]
	v_mfma_f32_16x16x32_bf16 v[78:81], v[174:177], v[214:217], v[78:81]
	v_mfma_f32_16x16x32_bf16 v[78:81], v[178:181], v[230:233], v[78:81]
	v_mfma_f32_16x16x32_bf16 v[70:73], v[166:169], v[234:237], v[70:73]
	v_mfma_f32_16x16x32_bf16 v[70:73], v[170:173], v[238:241], v[70:73]
	v_mfma_f32_16x16x32_bf16 v[66:69], v[174:177], v[234:237], v[66:69]
	v_mfma_f32_16x16x32_bf16 v[66:69], v[178:181], v[238:241], v[66:69]
	s_setprio 0
	s_barrier
	s_add_i32 s30, s40, s10
	v_lshl_add_u64 v[144:145], s[54:55], 0, v[194:195]
	s_mov_b32 m0, s30
	ds_read_b128 v[182:185], v148 offset:16384
	ds_read_b128 v[186:189], v148 offset:17408
	ds_read_b128 v[190:193], v148 offset:18432
	ds_read_b128 v[210:213], v148 offset:19456
	ds_read_b128 v[214:217], v148 offset:20480
	ds_read_b128 v[230:233], v148 offset:21504
	ds_read_b128 v[234:237], v148 offset:22528
	ds_read_b128 v[238:241], v148 offset:23552
	global_load_lds_dwordx4 v[144:145], off
	s_add_i32 m0, s30, 0x2000
	s_add_u32 s30, s54, 0x80000
	v_lshl_add_u64 v[218:219], s[54:55], 0, v[130:131]
	s_addc_u32 s31, s55, 0
	s_add_i32 s40, s44, s10
	global_load_lds_dwordx4 v[218:219], off
	v_lshl_add_u64 v[242:243], s[30:31], 0, v[194:195]
	s_mov_b32 m0, s40
	v_lshl_add_u64 v[244:245], vcc, 0, v[132:133]
	global_load_lds_dwordx4 v[242:243], off
	v_lshl_add_u64 v[242:243], s[30:31], 0, v[130:131]
	s_add_i32 m0, s40, 0x2000
	s_nop 0
	global_load_lds_dwordx4 v[242:243], off
	v_lshl_add_u64 v[242:243], vcc, 0, v[134:135]
	s_mov_b32 m0, s15
	s_nop 0
	global_load_lds_dwordx4 v[242:243], off
	s_mov_b32 m0, s16
	s_nop 0
	global_load_lds_dwordx4 v[244:245], off
	s_waitcnt vmcnt(8)
	s_waitcnt lgkmcnt(0)
	s_barrier
	s_setprio 1
	s_waitcnt lgkmcnt(0)
	v_mfma_f32_16x16x32_bf16 v[62:65], v[150:153], v[182:185], v[62:65]
	v_mfma_f32_16x16x32_bf16 v[62:65], v[154:157], v[186:189], v[62:65]
	v_mfma_f32_16x16x32_bf16 v[58:61], v[158:161], v[182:185], v[58:61]
	v_mfma_f32_16x16x32_bf16 v[58:61], v[162:165], v[186:189], v[58:61]
	v_mfma_f32_16x16x32_bf16 v[50:53], v[150:153], v[190:193], v[50:53]
	v_mfma_f32_16x16x32_bf16 v[50:53], v[154:157], v[210:213], v[50:53]
	v_mfma_f32_16x16x32_bf16 v[42:45], v[158:161], v[190:193], v[42:45]
	v_mfma_f32_16x16x32_bf16 v[42:45], v[162:165], v[210:213], v[42:45]
	v_mfma_f32_16x16x32_bf16 v[34:37], v[150:153], v[214:217], v[34:37]
	v_mfma_f32_16x16x32_bf16 v[34:37], v[154:157], v[230:233], v[34:37]
	v_mfma_f32_16x16x32_bf16 v[26:29], v[158:161], v[214:217], v[26:29]
	v_mfma_f32_16x16x32_bf16 v[26:29], v[162:165], v[230:233], v[26:29]
	v_mfma_f32_16x16x32_bf16 v[18:21], v[150:153], v[234:237], v[18:21]
	v_mfma_f32_16x16x32_bf16 v[18:21], v[154:157], v[238:241], v[18:21]
	v_mfma_f32_16x16x32_bf16 v[10:13], v[158:161], v[234:237], v[10:13]
	v_mfma_f32_16x16x32_bf16 v[10:13], v[162:165], v[238:241], v[10:13]
	s_setprio 0
	s_setprio 1
	v_mfma_f32_16x16x32_bf16 v[54:57], v[166:169], v[182:185], v[54:57]
	v_mfma_f32_16x16x32_bf16 v[54:57], v[170:173], v[186:189], v[54:57]
	v_mfma_f32_16x16x32_bf16 v[46:49], v[174:177], v[182:185], v[46:49]
	v_mfma_f32_16x16x32_bf16 v[46:49], v[178:181], v[186:189], v[46:49]
	v_mfma_f32_16x16x32_bf16 v[38:41], v[166:169], v[190:193], v[38:41]
	v_mfma_f32_16x16x32_bf16 v[38:41], v[170:173], v[210:213], v[38:41]
	v_mfma_f32_16x16x32_bf16 v[30:33], v[174:177], v[190:193], v[30:33]
	v_mfma_f32_16x16x32_bf16 v[30:33], v[178:181], v[210:213], v[30:33]
	v_mfma_f32_16x16x32_bf16 v[22:25], v[166:169], v[214:217], v[22:25]
	v_mfma_f32_16x16x32_bf16 v[22:25], v[170:173], v[230:233], v[22:25]
	v_mfma_f32_16x16x32_bf16 v[14:17], v[174:177], v[214:217], v[14:17]
	v_mfma_f32_16x16x32_bf16 v[14:17], v[178:181], v[230:233], v[14:17]
	v_mfma_f32_16x16x32_bf16 v[6:9], v[166:169], v[234:237], v[6:9]
	v_mfma_f32_16x16x32_bf16 v[6:9], v[170:173], v[238:241], v[6:9]
	v_mfma_f32_16x16x32_bf16 v[2:5], v[174:177], v[234:237], v[2:5]
	v_mfma_f32_16x16x32_bf16 v[2:5], v[178:181], v[238:241], v[2:5]
	s_setprio 0
	s_barrier
	s_add_i32 s40, 0, 0x18000
	v_add_u32_e32 v142, s40, v146
	s_add_i32 s44, 0, 0x1c000
	ds_read_b128 v[150:153], v142
	ds_read_b128 v[154:157], v142 offset:1024
	ds_read_b128 v[158:161], v142 offset:2048
	ds_read_b128 v[162:165], v142 offset:3072
	v_add_u32_e32 v142, s44, v146
	ds_read_b128 v[166:169], v142
	ds_read_b128 v[170:173], v142 offset:1024
	ds_read_b128 v[174:177], v142 offset:2048
	ds_read_b128 v[178:181], v142 offset:3072
	s_add_u32 s30, vcc_lo, 0x80000
	s_addc_u32 s31, vcc_hi, 0
	s_mov_b32 m0, s17
	v_lshl_add_u64 v[246:247], s[30:31], 0, v[134:135]
	ds_read_b128 v[182:185], v148 offset:32768
	ds_read_b128 v[186:189], v148 offset:33792
	ds_read_b128 v[190:193], v148 offset:34816
	ds_read_b128 v[210:213], v148 offset:35840
	ds_read_b128 v[214:217], v148 offset:36864
	ds_read_b128 v[230:233], v148 offset:37888
	ds_read_b128 v[234:237], v148 offset:38912
	ds_read_b128 v[238:241], v148 offset:39936
	global_load_lds_dwordx4 v[246:247], off
	v_lshl_add_u64 v[246:247], s[30:31], 0, v[132:133]
	s_mov_b32 m0, s18
	s_nop 0
	global_load_lds_dwordx4 v[246:247], off
	s_waitcnt vmcnt(8)
	s_waitcnt lgkmcnt(0)
	s_barrier
	s_setprio 1
	s_waitcnt lgkmcnt(0)
	v_mfma_f32_16x16x32_bf16 v[126:129], v[150:153], v[182:185], v[126:129]
	v_mfma_f32_16x16x32_bf16 v[126:129], v[154:157], v[186:189], v[126:129]
	v_mfma_f32_16x16x32_bf16 v[122:125], v[158:161], v[182:185], v[122:125]
	v_mfma_f32_16x16x32_bf16 v[122:125], v[162:165], v[186:189], v[122:125]
	v_mfma_f32_16x16x32_bf16 v[114:117], v[150:153], v[190:193], v[114:117]
	v_mfma_f32_16x16x32_bf16 v[114:117], v[154:157], v[210:213], v[114:117]
	v_mfma_f32_16x16x32_bf16 v[106:109], v[158:161], v[190:193], v[106:109]
	v_mfma_f32_16x16x32_bf16 v[106:109], v[162:165], v[210:213], v[106:109]
	v_mfma_f32_16x16x32_bf16 v[98:101], v[150:153], v[214:217], v[98:101]
	v_mfma_f32_16x16x32_bf16 v[98:101], v[154:157], v[230:233], v[98:101]
	v_mfma_f32_16x16x32_bf16 v[90:93], v[158:161], v[214:217], v[90:93]
	v_mfma_f32_16x16x32_bf16 v[90:93], v[162:165], v[230:233], v[90:93]
	v_mfma_f32_16x16x32_bf16 v[82:85], v[150:153], v[234:237], v[82:85]
	v_mfma_f32_16x16x32_bf16 v[82:85], v[154:157], v[238:241], v[82:85]
	v_mfma_f32_16x16x32_bf16 v[74:77], v[158:161], v[234:237], v[74:77]
	v_mfma_f32_16x16x32_bf16 v[74:77], v[162:165], v[238:241], v[74:77]
	s_setprio 0
	s_setprio 1
	v_mfma_f32_16x16x32_bf16 v[118:121], v[166:169], v[182:185], v[118:121]
	v_mfma_f32_16x16x32_bf16 v[118:121], v[170:173], v[186:189], v[118:121]
	v_mfma_f32_16x16x32_bf16 v[110:113], v[174:177], v[182:185], v[110:113]
	v_mfma_f32_16x16x32_bf16 v[110:113], v[178:181], v[186:189], v[110:113]
	v_mfma_f32_16x16x32_bf16 v[102:105], v[166:169], v[190:193], v[102:105]
	v_mfma_f32_16x16x32_bf16 v[102:105], v[170:173], v[210:213], v[102:105]
	v_mfma_f32_16x16x32_bf16 v[94:97], v[174:177], v[190:193], v[94:97]
	v_mfma_f32_16x16x32_bf16 v[94:97], v[178:181], v[210:213], v[94:97]
	v_mfma_f32_16x16x32_bf16 v[86:89], v[166:169], v[214:217], v[86:89]
	v_mfma_f32_16x16x32_bf16 v[86:89], v[170:173], v[230:233], v[86:89]
	v_mfma_f32_16x16x32_bf16 v[78:81], v[174:177], v[214:217], v[78:81]
	v_mfma_f32_16x16x32_bf16 v[78:81], v[178:181], v[230:233], v[78:81]
	v_mfma_f32_16x16x32_bf16 v[70:73], v[166:169], v[234:237], v[70:73]
	v_mfma_f32_16x16x32_bf16 v[70:73], v[170:173], v[238:241], v[70:73]
	v_mfma_f32_16x16x32_bf16 v[66:69], v[174:177], v[234:237], v[66:69]
	v_mfma_f32_16x16x32_bf16 v[66:69], v[178:181], v[238:241], v[66:69]
	s_setprio 0
	s_barrier
	s_add_i32 s30, s40, s10
	v_lshl_add_u64 v[144:145], v[144:145], 0, s[56:57]
	s_mov_b32 m0, s30
	ds_read_b128 v[182:185], v148 offset:49152
	ds_read_b128 v[186:189], v148 offset:50176
	ds_read_b128 v[190:193], v148 offset:51200
	ds_read_b128 v[210:213], v148 offset:52224
	ds_read_b128 v[214:217], v148 offset:53248
	ds_read_b128 v[230:233], v148 offset:54272
	ds_read_b128 v[234:237], v148 offset:55296
	ds_read_b128 v[238:241], v148 offset:56320
	global_load_lds_dwordx4 v[144:145], off
	s_add_i32 m0, s30, 0x2000
	s_add_u32 s30, s54, 0x80080
	v_lshl_add_u64 v[144:145], v[218:219], 0, s[56:57]
	s_addc_u32 s31, s55, 0
	s_add_i32 s40, s44, s10
	global_load_lds_dwordx4 v[144:145], off
	v_lshl_add_u64 v[144:145], s[30:31], 0, v[194:195]
	s_mov_b32 m0, s40
	s_nop 0
	global_load_lds_dwordx4 v[144:145], off
	v_lshl_add_u64 v[144:145], s[30:31], 0, v[130:131]
	s_add_i32 m0, s40, 0x2000
	s_nop 0
	global_load_lds_dwordx4 v[144:145], off
	v_lshl_add_u64 v[144:145], v[242:243], 0, s[56:57]
	s_mov_b32 m0, s21
	s_nop 0
	global_load_lds_dwordx4 v[144:145], off
	v_lshl_add_u64 v[144:145], v[244:245], 0, s[56:57]
	s_mov_b32 m0, s22
	s_nop 0
	global_load_lds_dwordx4 v[144:145], off
	s_waitcnt vmcnt(8)
	s_waitcnt lgkmcnt(0)
	s_barrier
	s_setprio 1
	s_waitcnt lgkmcnt(0)
	v_mfma_f32_16x16x32_bf16 v[62:65], v[150:153], v[182:185], v[62:65]
	v_mfma_f32_16x16x32_bf16 v[62:65], v[154:157], v[186:189], v[62:65]
	v_mfma_f32_16x16x32_bf16 v[58:61], v[158:161], v[182:185], v[58:61]
	v_mfma_f32_16x16x32_bf16 v[58:61], v[162:165], v[186:189], v[58:61]
	v_mfma_f32_16x16x32_bf16 v[50:53], v[150:153], v[190:193], v[50:53]
	v_mfma_f32_16x16x32_bf16 v[50:53], v[154:157], v[210:213], v[50:53]
	v_mfma_f32_16x16x32_bf16 v[42:45], v[158:161], v[190:193], v[42:45]
	v_mfma_f32_16x16x32_bf16 v[42:45], v[162:165], v[210:213], v[42:45]
	v_mfma_f32_16x16x32_bf16 v[34:37], v[150:153], v[214:217], v[34:37]
	v_mfma_f32_16x16x32_bf16 v[34:37], v[154:157], v[230:233], v[34:37]
	v_mfma_f32_16x16x32_bf16 v[26:29], v[158:161], v[214:217], v[26:29]
	v_mfma_f32_16x16x32_bf16 v[26:29], v[162:165], v[230:233], v[26:29]
	v_mfma_f32_16x16x32_bf16 v[18:21], v[150:153], v[234:237], v[18:21]
	v_mfma_f32_16x16x32_bf16 v[18:21], v[154:157], v[238:241], v[18:21]
	v_mfma_f32_16x16x32_bf16 v[10:13], v[158:161], v[234:237], v[10:13]
	v_mfma_f32_16x16x32_bf16 v[10:13], v[162:165], v[238:241], v[10:13]
	s_setprio 0
	s_setprio 1
	v_mfma_f32_16x16x32_bf16 v[54:57], v[166:169], v[182:185], v[54:57]
	v_mfma_f32_16x16x32_bf16 v[54:57], v[170:173], v[186:189], v[54:57]
	v_mfma_f32_16x16x32_bf16 v[46:49], v[174:177], v[182:185], v[46:49]
	v_mfma_f32_16x16x32_bf16 v[46:49], v[178:181], v[186:189], v[46:49]
	v_mfma_f32_16x16x32_bf16 v[38:41], v[166:169], v[190:193], v[38:41]
	v_mfma_f32_16x16x32_bf16 v[38:41], v[170:173], v[210:213], v[38:41]
	v_mfma_f32_16x16x32_bf16 v[30:33], v[174:177], v[190:193], v[30:33]
	v_mfma_f32_16x16x32_bf16 v[30:33], v[178:181], v[210:213], v[30:33]
	v_mfma_f32_16x16x32_bf16 v[22:25], v[166:169], v[214:217], v[22:25]
	v_mfma_f32_16x16x32_bf16 v[22:25], v[170:173], v[230:233], v[22:25]
	v_mfma_f32_16x16x32_bf16 v[14:17], v[174:177], v[214:217], v[14:17]
	v_mfma_f32_16x16x32_bf16 v[14:17], v[178:181], v[230:233], v[14:17]
	v_mfma_f32_16x16x32_bf16 v[6:9], v[166:169], v[234:237], v[6:9]
	v_mfma_f32_16x16x32_bf16 v[6:9], v[170:173], v[238:241], v[6:9]
	v_mfma_f32_16x16x32_bf16 v[2:5], v[174:177], v[234:237], v[2:5]
	v_mfma_f32_16x16x32_bf16 v[2:5], v[178:181], v[238:241], v[2:5]
	s_setprio 0
	s_barrier
	s_add_i32 s29, s29, 2
	s_add_u32 s27, s27, 0x100
	s_addc_u32 s28, s28, 0
	s_add_u32 s90, s90, 0x100
	s_addc_u32 s91, s91, 0
	s_cmp_gt_u32 s29, 29
	s_cbranch_scc0 .LBB0_1207
	s_and_b64 vcc, exec, s[36:37]
	s_cbranch_vccz .LBB0_1210
	s_barrier

.LBB0_1465:
	s_add_u32 s27, s88, 0xfff80080
	s_addc_u32 s28, s89, -1
	s_add_i32 s29, 0, 0x10000
	s_cmp_eq_u32 s26, 28
	s_cselect_b32 s91, s20, s28
	s_cselect_b32 s90, s21, s27
	v_add_u32_e32 v140, s29, v143
	s_cselect_b32 s55, s22, s25
	s_cselect_b32 s54, s23, s24
	s_add_i32 s27, 0, 0x14000
	ds_read_b128 v[146:149], v140
	ds_read_b128 v[150:153], v140 offset:1024
	ds_read_b128 v[154:157], v140 offset:2048
	ds_read_b128 v[158:161], v140 offset:3072
	v_add_u32_e32 v140, s27, v143
	ds_read_b128 v[162:165], v140
	ds_read_b128 v[166:169], v140 offset:1024
	ds_read_b128 v[170:173], v140 offset:2048
	ds_read_b128 v[174:177], v140 offset:3072
	v_lshl_add_u64 v[140:141], s[88:89], 0, v[138:139]
	s_add_i32 m0, s12, 0xc000
	ds_read_b128 v[178:181], v145
	ds_read_b128 v[182:185], v145 offset:1024
	ds_read_b128 v[186:189], v145 offset:2048
	ds_read_b128 v[190:193], v145 offset:3072
	ds_read_b128 v[210:213], v145 offset:4096
	ds_read_b128 v[214:217], v145 offset:5120
	ds_read_b128 v[230:233], v145 offset:6144
	ds_read_b128 v[234:237], v145 offset:7168
	global_load_lds_dwordx4 v[140:141], off
	v_lshl_add_u64 v[140:141], s[88:89], 0, v[136:137]
	s_add_i32 m0, s12, 0xe000
	s_nop 0
	global_load_lds_dwordx4 v[140:141], off
	s_waitcnt vmcnt(8)
	s_waitcnt lgkmcnt(0)
	s_barrier
	s_setprio 1
	s_waitcnt lgkmcnt(0)
	v_mfma_f32_16x16x32_bf16 v[126:129], v[146:149], v[178:181], v[126:129]
	v_mfma_f32_16x16x32_bf16 v[126:129], v[150:153], v[182:185], v[126:129]
	v_mfma_f32_16x16x32_bf16 v[122:125], v[154:157], v[178:181], v[122:125]
	v_mfma_f32_16x16x32_bf16 v[122:125], v[158:161], v[182:185], v[122:125]
	v_mfma_f32_16x16x32_bf16 v[118:121], v[146:149], v[186:189], v[118:121]
	v_mfma_f32_16x16x32_bf16 v[118:121], v[150:153], v[190:193], v[118:121]
	v_mfma_f32_16x16x32_bf16 v[110:113], v[154:157], v[186:189], v[110:113]
	v_mfma_f32_16x16x32_bf16 v[110:113], v[158:161], v[190:193], v[110:113]
	v_mfma_f32_16x16x32_bf16 v[102:105], v[146:149], v[210:213], v[102:105]
	v_mfma_f32_16x16x32_bf16 v[102:105], v[150:153], v[214:217], v[102:105]
	v_mfma_f32_16x16x32_bf16 v[94:97], v[154:157], v[210:213], v[94:97]
	v_mfma_f32_16x16x32_bf16 v[94:97], v[158:161], v[214:217], v[94:97]
	v_mfma_f32_16x16x32_bf16 v[86:89], v[146:149], v[230:233], v[86:89]
	v_mfma_f32_16x16x32_bf16 v[86:89], v[150:153], v[234:237], v[86:89]
	v_mfma_f32_16x16x32_bf16 v[78:81], v[154:157], v[230:233], v[78:81]
	v_mfma_f32_16x16x32_bf16 v[78:81], v[158:161], v[234:237], v[78:81]
	s_setprio 0
	s_setprio 1
	v_mfma_f32_16x16x32_bf16 v[114:117], v[162:165], v[178:181], v[114:117]
	v_mfma_f32_16x16x32_bf16 v[114:117], v[166:169], v[182:185], v[114:117]
	v_mfma_f32_16x16x32_bf16 v[106:109], v[170:173], v[178:181], v[106:109]
	v_mfma_f32_16x16x32_bf16 v[106:109], v[174:177], v[182:185], v[106:109]
	v_mfma_f32_16x16x32_bf16 v[98:101], v[162:165], v[186:189], v[98:101]
	v_mfma_f32_16x16x32_bf16 v[98:101], v[166:169], v[190:193], v[98:101]
	v_mfma_f32_16x16x32_bf16 v[90:93], v[170:173], v[186:189], v[90:93]
	v_mfma_f32_16x16x32_bf16 v[90:93], v[174:177], v[190:193], v[90:93]
	v_mfma_f32_16x16x32_bf16 v[82:85], v[162:165], v[210:213], v[82:85]
	v_mfma_f32_16x16x32_bf16 v[82:85], v[166:169], v[214:217], v[82:85]
	v_mfma_f32_16x16x32_bf16 v[74:77], v[170:173], v[210:213], v[74:77]
	v_mfma_f32_16x16x32_bf16 v[74:77], v[174:177], v[214:217], v[74:77]
	v_mfma_f32_16x16x32_bf16 v[70:73], v[162:165], v[230:233], v[70:73]
	v_mfma_f32_16x16x32_bf16 v[70:73], v[166:169], v[234:237], v[70:73]
	v_mfma_f32_16x16x32_bf16 v[66:69], v[170:173], v[230:233], v[66:69]
	v_mfma_f32_16x16x32_bf16 v[66:69], v[174:177], v[234:237], v[66:69]
	s_setprio 0
	s_barrier
	s_add_i32 s28, s29, s11
	v_lshl_add_u64 v[140:141], s[54:55], 0, v[194:195]
	s_mov_b32 m0, s28
	ds_read_b128 v[178:181], v145 offset:16384
	ds_read_b128 v[182:185], v145 offset:17408
	ds_read_b128 v[186:189], v145 offset:18432
	ds_read_b128 v[190:193], v145 offset:19456
	ds_read_b128 v[210:213], v145 offset:20480
	ds_read_b128 v[214:217], v145 offset:21504
	ds_read_b128 v[230:233], v145 offset:22528
	ds_read_b128 v[234:237], v145 offset:23552
	global_load_lds_dwordx4 v[140:141], off
	s_add_i32 m0, s28, 0x2000
	s_add_u32 s28, s54, 0x80000
	v_lshl_add_u64 v[218:219], s[54:55], 0, v[134:135]
	s_addc_u32 s29, s55, 0
	s_add_i32 s27, s27, s11
	global_load_lds_dwordx4 v[218:219], off
	v_lshl_add_u64 v[238:239], s[28:29], 0, v[194:195]
	s_mov_b32 m0, s27
	v_lshl_add_u64 v[240:241], s[90:91], 0, v[132:133]
	global_load_lds_dwordx4 v[238:239], off
	v_lshl_add_u64 v[238:239], s[28:29], 0, v[134:135]
	s_add_i32 m0, s27, 0x2000
	s_nop 0
	global_load_lds_dwordx4 v[238:239], off
	v_lshl_add_u64 v[238:239], s[90:91], 0, v[130:131]
	s_mov_b32 m0, s12
	s_nop 0
	global_load_lds_dwordx4 v[238:239], off
	s_mov_b32 m0, s13
	s_nop 0
	global_load_lds_dwordx4 v[240:241], off
	s_waitcnt vmcnt(8)
	s_waitcnt lgkmcnt(0)
	s_barrier
	s_setprio 1
	s_waitcnt lgkmcnt(0)
	v_mfma_f32_16x16x32_bf16 v[62:65], v[146:149], v[178:181], v[62:65]
	v_mfma_f32_16x16x32_bf16 v[62:65], v[150:153], v[182:185], v[62:65]
	v_mfma_f32_16x16x32_bf16 v[58:61], v[154:157], v[178:181], v[58:61]
	v_mfma_f32_16x16x32_bf16 v[58:61], v[158:161], v[182:185], v[58:61]
	v_mfma_f32_16x16x32_bf16 v[54:57], v[146:149], v[186:189], v[54:57]
	v_mfma_f32_16x16x32_bf16 v[54:57], v[150:153], v[190:193], v[54:57]
	v_mfma_f32_16x16x32_bf16 v[46:49], v[154:157], v[186:189], v[46:49]
	v_mfma_f32_16x16x32_bf16 v[46:49], v[158:161], v[190:193], v[46:49]
	v_mfma_f32_16x16x32_bf16 v[38:41], v[146:149], v[210:213], v[38:41]
	v_mfma_f32_16x16x32_bf16 v[38:41], v[150:153], v[214:217], v[38:41]
	v_mfma_f32_16x16x32_bf16 v[30:33], v[154:157], v[210:213], v[30:33]
	v_mfma_f32_16x16x32_bf16 v[30:33], v[158:161], v[214:217], v[30:33]
	v_mfma_f32_16x16x32_bf16 v[22:25], v[146:149], v[230:233], v[22:25]
	v_mfma_f32_16x16x32_bf16 v[22:25], v[150:153], v[234:237], v[22:25]
	v_mfma_f32_16x16x32_bf16 v[14:17], v[154:157], v[230:233], v[14:17]
	v_mfma_f32_16x16x32_bf16 v[14:17], v[158:161], v[234:237], v[14:17]
	s_setprio 0
	s_setprio 1
	v_mfma_f32_16x16x32_bf16 v[50:53], v[162:165], v[178:181], v[50:53]
	v_mfma_f32_16x16x32_bf16 v[50:53], v[166:169], v[182:185], v[50:53]
	v_mfma_f32_16x16x32_bf16 v[42:45], v[170:173], v[178:181], v[42:45]
	v_mfma_f32_16x16x32_bf16 v[42:45], v[174:177], v[182:185], v[42:45]
	v_mfma_f32_16x16x32_bf16 v[34:37], v[162:165], v[186:189], v[34:37]
	v_mfma_f32_16x16x32_bf16 v[34:37], v[166:169], v[190:193], v[34:37]
	v_mfma_f32_16x16x32_bf16 v[26:29], v[170:173], v[186:189], v[26:29]
	v_mfma_f32_16x16x32_bf16 v[26:29], v[174:177], v[190:193], v[26:29]
	v_mfma_f32_16x16x32_bf16 v[18:21], v[162:165], v[210:213], v[18:21]
	v_mfma_f32_16x16x32_bf16 v[18:21], v[166:169], v[214:217], v[18:21]
	v_mfma_f32_16x16x32_bf16 v[10:13], v[170:173], v[210:213], v[10:13]
	v_mfma_f32_16x16x32_bf16 v[10:13], v[174:177], v[214:217], v[10:13]
	v_mfma_f32_16x16x32_bf16 v[6:9], v[162:165], v[230:233], v[6:9]
	v_mfma_f32_16x16x32_bf16 v[6:9], v[166:169], v[234:237], v[6:9]
	v_mfma_f32_16x16x32_bf16 v[2:5], v[170:173], v[230:233], v[2:5]
	v_mfma_f32_16x16x32_bf16 v[2:5], v[174:177], v[234:237], v[2:5]
	s_setprio 0
	s_barrier
	s_add_i32 s27, 0, 0x18000
	s_add_i32 s30, 0, 0x1c000
	v_add_u32_e32 v158, s27, v143
	v_add_u32_e32 v174, s30, v143
	ds_read_b128 v[146:149], v158
	ds_read_b128 v[150:153], v158 offset:1024
	ds_read_b128 v[154:157], v158 offset:2048
	ds_read_b128 v[158:161], v158 offset:3072
	ds_read_b128 v[162:165], v174
	ds_read_b128 v[166:169], v174 offset:1024
	ds_read_b128 v[170:173], v174 offset:2048
	ds_read_b128 v[174:177], v174 offset:3072
	s_add_u32 s28, s90, 0x80000
	s_addc_u32 s29, s91, 0
	s_mov_b32 m0, s14
	v_lshl_add_u64 v[242:243], s[28:29], 0, v[130:131]
	ds_read_b128 v[178:181], v145 offset:32768
	ds_read_b128 v[182:185], v145 offset:33792
	ds_read_b128 v[186:189], v145 offset:34816
	ds_read_b128 v[190:193], v145 offset:35840
	ds_read_b128 v[210:213], v145 offset:36864
	ds_read_b128 v[214:217], v145 offset:37888
	ds_read_b128 v[230:233], v145 offset:38912
	ds_read_b128 v[234:237], v145 offset:39936
	global_load_lds_dwordx4 v[242:243], off
	v_lshl_add_u64 v[242:243], s[28:29], 0, v[132:133]
	s_mov_b32 m0, s15
	s_nop 0
	global_load_lds_dwordx4 v[242:243], off
	s_waitcnt vmcnt(8)
	s_waitcnt lgkmcnt(0)
	s_barrier
	s_setprio 1
	s_waitcnt lgkmcnt(0)
	v_mfma_f32_16x16x32_bf16 v[126:129], v[146:149], v[178:181], v[126:129]
	v_mfma_f32_16x16x32_bf16 v[126:129], v[150:153], v[182:185], v[126:129]
	v_mfma_f32_16x16x32_bf16 v[122:125], v[154:157], v[178:181], v[122:125]
	v_mfma_f32_16x16x32_bf16 v[122:125], v[158:161], v[182:185], v[122:125]
	v_mfma_f32_16x16x32_bf16 v[118:121], v[146:149], v[186:189], v[118:121]
	v_mfma_f32_16x16x32_bf16 v[118:121], v[150:153], v[190:193], v[118:121]
	v_mfma_f32_16x16x32_bf16 v[110:113], v[154:157], v[186:189], v[110:113]
	v_mfma_f32_16x16x32_bf16 v[110:113], v[158:161], v[190:193], v[110:113]
	v_mfma_f32_16x16x32_bf16 v[102:105], v[146:149], v[210:213], v[102:105]
	v_mfma_f32_16x16x32_bf16 v[102:105], v[150:153], v[214:217], v[102:105]
	v_mfma_f32_16x16x32_bf16 v[94:97], v[154:157], v[210:213], v[94:97]
	v_mfma_f32_16x16x32_bf16 v[94:97], v[158:161], v[214:217], v[94:97]
	v_mfma_f32_16x16x32_bf16 v[86:89], v[146:149], v[230:233], v[86:89]
	v_mfma_f32_16x16x32_bf16 v[86:89], v[150:153], v[234:237], v[86:89]
	v_mfma_f32_16x16x32_bf16 v[78:81], v[154:157], v[230:233], v[78:81]
	v_mfma_f32_16x16x32_bf16 v[78:81], v[158:161], v[234:237], v[78:81]
	s_setprio 0
	s_setprio 1
	v_mfma_f32_16x16x32_bf16 v[114:117], v[162:165], v[178:181], v[114:117]
	v_mfma_f32_16x16x32_bf16 v[114:117], v[166:169], v[182:185], v[114:117]
	v_mfma_f32_16x16x32_bf16 v[106:109], v[170:173], v[178:181], v[106:109]
	v_mfma_f32_16x16x32_bf16 v[106:109], v[174:177], v[182:185], v[106:109]
	v_mfma_f32_16x16x32_bf16 v[98:101], v[162:165], v[186:189], v[98:101]
	v_mfma_f32_16x16x32_bf16 v[98:101], v[166:169], v[190:193], v[98:101]
	v_mfma_f32_16x16x32_bf16 v[90:93], v[170:173], v[186:189], v[90:93]
	v_mfma_f32_16x16x32_bf16 v[90:93], v[174:177], v[190:193], v[90:93]
	v_mfma_f32_16x16x32_bf16 v[82:85], v[162:165], v[210:213], v[82:85]
	v_mfma_f32_16x16x32_bf16 v[82:85], v[166:169], v[214:217], v[82:85]
	v_mfma_f32_16x16x32_bf16 v[74:77], v[170:173], v[210:213], v[74:77]
	v_mfma_f32_16x16x32_bf16 v[74:77], v[174:177], v[214:217], v[74:77]
	v_mfma_f32_16x16x32_bf16 v[70:73], v[162:165], v[230:233], v[70:73]
	v_mfma_f32_16x16x32_bf16 v[70:73], v[166:169], v[234:237], v[70:73]
	v_mfma_f32_16x16x32_bf16 v[66:69], v[170:173], v[230:233], v[66:69]
	v_mfma_f32_16x16x32_bf16 v[66:69], v[174:177], v[234:237], v[66:69]
	s_setprio 0
	s_barrier
	s_add_i32 s27, s27, s11
	v_lshl_add_u64 v[140:141], v[140:141], 0, s[56:57]
	s_mov_b32 m0, s27
	ds_read_b128 v[178:181], v145 offset:49152
	ds_read_b128 v[182:185], v145 offset:50176
	ds_read_b128 v[186:189], v145 offset:51200
	ds_read_b128 v[190:193], v145 offset:52224
	ds_read_b128 v[210:213], v145 offset:53248
	ds_read_b128 v[214:217], v145 offset:54272
	ds_read_b128 v[230:233], v145 offset:55296
	ds_read_b128 v[234:237], v145 offset:56320
	global_load_lds_dwordx4 v[140:141], off
	s_add_i32 m0, s27, 0x2000
	s_add_u32 s28, s54, 0x80080
	v_lshl_add_u64 v[140:141], v[218:219], 0, s[56:57]
	s_addc_u32 s29, s55, 0
	s_add_i32 s27, s30, s11
	global_load_lds_dwordx4 v[140:141], off
	v_lshl_add_u64 v[140:141], s[28:29], 0, v[194:195]
	s_mov_b32 m0, s27
	s_nop 0
	global_load_lds_dwordx4 v[140:141], off
	v_lshl_add_u64 v[140:141], s[28:29], 0, v[134:135]
	s_add_i32 m0, s27, 0x2000
	s_nop 0
	global_load_lds_dwordx4 v[140:141], off
	v_lshl_add_u64 v[140:141], v[238:239], 0, s[56:57]
	s_mov_b32 m0, s16
	s_nop 0
	global_load_lds_dwordx4 v[140:141], off
	v_lshl_add_u64 v[140:141], v[240:241], 0, s[56:57]
	s_mov_b32 m0, s17
	s_nop 0
	global_load_lds_dwordx4 v[140:141], off
	s_waitcnt vmcnt(8)
	s_waitcnt lgkmcnt(0)
	s_barrier
	s_setprio 1
	s_waitcnt lgkmcnt(0)
	v_mfma_f32_16x16x32_bf16 v[62:65], v[146:149], v[178:181], v[62:65]
	v_mfma_f32_16x16x32_bf16 v[62:65], v[150:153], v[182:185], v[62:65]
	v_mfma_f32_16x16x32_bf16 v[58:61], v[154:157], v[178:181], v[58:61]
	v_mfma_f32_16x16x32_bf16 v[58:61], v[158:161], v[182:185], v[58:61]
	v_mfma_f32_16x16x32_bf16 v[54:57], v[146:149], v[186:189], v[54:57]
	v_mfma_f32_16x16x32_bf16 v[54:57], v[150:153], v[190:193], v[54:57]
	v_mfma_f32_16x16x32_bf16 v[46:49], v[154:157], v[186:189], v[46:49]
	v_mfma_f32_16x16x32_bf16 v[46:49], v[158:161], v[190:193], v[46:49]
	v_mfma_f32_16x16x32_bf16 v[38:41], v[146:149], v[210:213], v[38:41]
	v_mfma_f32_16x16x32_bf16 v[38:41], v[150:153], v[214:217], v[38:41]
	v_mfma_f32_16x16x32_bf16 v[30:33], v[154:157], v[210:213], v[30:33]
	v_mfma_f32_16x16x32_bf16 v[30:33], v[158:161], v[214:217], v[30:33]
	v_mfma_f32_16x16x32_bf16 v[22:25], v[146:149], v[230:233], v[22:25]
	v_mfma_f32_16x16x32_bf16 v[22:25], v[150:153], v[234:237], v[22:25]
	v_mfma_f32_16x16x32_bf16 v[14:17], v[154:157], v[230:233], v[14:17]
	v_mfma_f32_16x16x32_bf16 v[14:17], v[158:161], v[234:237], v[14:17]
	s_setprio 0
	s_setprio 1
	v_mfma_f32_16x16x32_bf16 v[50:53], v[162:165], v[178:181], v[50:53]
	v_mfma_f32_16x16x32_bf16 v[50:53], v[166:169], v[182:185], v[50:53]
	v_mfma_f32_16x16x32_bf16 v[42:45], v[170:173], v[178:181], v[42:45]
	v_mfma_f32_16x16x32_bf16 v[42:45], v[174:177], v[182:185], v[42:45]
	v_mfma_f32_16x16x32_bf16 v[34:37], v[162:165], v[186:189], v[34:37]
	v_mfma_f32_16x16x32_bf16 v[34:37], v[166:169], v[190:193], v[34:37]
	v_mfma_f32_16x16x32_bf16 v[26:29], v[170:173], v[186:189], v[26:29]
	v_mfma_f32_16x16x32_bf16 v[26:29], v[174:177], v[190:193], v[26:29]
	v_mfma_f32_16x16x32_bf16 v[18:21], v[162:165], v[210:213], v[18:21]
	v_mfma_f32_16x16x32_bf16 v[18:21], v[166:169], v[214:217], v[18:21]
	v_mfma_f32_16x16x32_bf16 v[10:13], v[170:173], v[210:213], v[10:13]
	v_mfma_f32_16x16x32_bf16 v[10:13], v[174:177], v[214:217], v[10:13]
	v_mfma_f32_16x16x32_bf16 v[6:9], v[162:165], v[230:233], v[6:9]
	v_mfma_f32_16x16x32_bf16 v[6:9], v[166:169], v[234:237], v[6:9]
	v_mfma_f32_16x16x32_bf16 v[2:5], v[170:173], v[230:233], v[2:5]
	v_mfma_f32_16x16x32_bf16 v[2:5], v[174:177], v[234:237], v[2:5]
	s_setprio 0
	s_barrier
	s_add_i32 s26, s26, 2
	s_add_u32 s24, s24, 0x100
	s_addc_u32 s25, s25, 0
	s_add_u32 s88, s88, 0x100
	s_addc_u32 s89, s89, 0
	s_cmp_gt_u32 s26, 29
	s_cbranch_scc0 .LBB0_1465
	s_and_b64 vcc, exec, s[44:45]
	s_cbranch_vccz .LBB0_1468
	s_barrier

.LBB0_1609:
	s_add_u32 s29, s90, 0xfff80080
	s_addc_u32 s30, s91, -1
	s_add_i32 s31, 0, 0x10000
	s_cmp_eq_u32 s28, 28
	s_cselect_b32 vcc_hi, s22, s30
	s_cselect_b32 vcc_lo, s23, s29
	v_add_u32_e32 v140, s31, v143
	s_cselect_b32 s55, s24, s27
	s_cselect_b32 s54, s25, s26
	s_add_i32 s29, 0, 0x14000
	ds_read_b128 v[146:149], v140
	ds_read_b128 v[150:153], v140 offset:1024
	ds_read_b128 v[154:157], v140 offset:2048
	ds_read_b128 v[158:161], v140 offset:3072
	v_add_u32_e32 v140, s29, v143
	ds_read_b128 v[162:165], v140
	ds_read_b128 v[166:169], v140 offset:1024
	ds_read_b128 v[170:173], v140 offset:2048
	ds_read_b128 v[174:177], v140 offset:3072
	v_lshl_add_u64 v[140:141], s[90:91], 0, v[138:139]
	s_add_i32 m0, s14, 0xc000
	ds_read_b128 v[178:181], v145
	ds_read_b128 v[182:185], v145 offset:1024
	ds_read_b128 v[186:189], v145 offset:2048
	ds_read_b128 v[190:193], v145 offset:3072
	ds_read_b128 v[210:213], v145 offset:4096
	ds_read_b128 v[214:217], v145 offset:5120
	ds_read_b128 v[230:233], v145 offset:6144
	ds_read_b128 v[234:237], v145 offset:7168
	global_load_lds_dwordx4 v[140:141], off
	v_lshl_add_u64 v[140:141], s[90:91], 0, v[136:137]
	s_add_i32 m0, s14, 0xe000
	s_nop 0
	global_load_lds_dwordx4 v[140:141], off
	s_waitcnt vmcnt(8)
	s_waitcnt lgkmcnt(0)
	s_barrier
	s_setprio 1
	s_waitcnt lgkmcnt(0)
	v_mfma_f32_16x16x32_bf16 v[126:129], v[146:149], v[178:181], v[126:129]
	v_mfma_f32_16x16x32_bf16 v[126:129], v[150:153], v[182:185], v[126:129]
	v_mfma_f32_16x16x32_bf16 v[122:125], v[154:157], v[178:181], v[122:125]
	v_mfma_f32_16x16x32_bf16 v[122:125], v[158:161], v[182:185], v[122:125]
	v_mfma_f32_16x16x32_bf16 v[110:113], v[146:149], v[186:189], v[110:113]
	v_mfma_f32_16x16x32_bf16 v[110:113], v[150:153], v[190:193], v[110:113]
	v_mfma_f32_16x16x32_bf16 v[106:109], v[154:157], v[186:189], v[106:109]
	v_mfma_f32_16x16x32_bf16 v[106:109], v[158:161], v[190:193], v[106:109]
	v_mfma_f32_16x16x32_bf16 v[94:97], v[146:149], v[210:213], v[94:97]
	v_mfma_f32_16x16x32_bf16 v[94:97], v[150:153], v[214:217], v[94:97]
	v_mfma_f32_16x16x32_bf16 v[90:93], v[154:157], v[210:213], v[90:93]
	v_mfma_f32_16x16x32_bf16 v[90:93], v[158:161], v[214:217], v[90:93]
	v_mfma_f32_16x16x32_bf16 v[78:81], v[146:149], v[230:233], v[78:81]
	v_mfma_f32_16x16x32_bf16 v[78:81], v[150:153], v[234:237], v[78:81]
	v_mfma_f32_16x16x32_bf16 v[74:77], v[154:157], v[230:233], v[74:77]
	v_mfma_f32_16x16x32_bf16 v[74:77], v[158:161], v[234:237], v[74:77]
	s_setprio 0
	s_setprio 1
	v_mfma_f32_16x16x32_bf16 v[118:121], v[162:165], v[178:181], v[118:121]
	v_mfma_f32_16x16x32_bf16 v[118:121], v[166:169], v[182:185], v[118:121]
	v_mfma_f32_16x16x32_bf16 v[114:117], v[170:173], v[178:181], v[114:117]
	v_mfma_f32_16x16x32_bf16 v[114:117], v[174:177], v[182:185], v[114:117]
	v_mfma_f32_16x16x32_bf16 v[102:105], v[162:165], v[186:189], v[102:105]
	v_mfma_f32_16x16x32_bf16 v[102:105], v[166:169], v[190:193], v[102:105]
	v_mfma_f32_16x16x32_bf16 v[98:101], v[170:173], v[186:189], v[98:101]
	v_mfma_f32_16x16x32_bf16 v[98:101], v[174:177], v[190:193], v[98:101]
	v_mfma_f32_16x16x32_bf16 v[86:89], v[162:165], v[210:213], v[86:89]
	v_mfma_f32_16x16x32_bf16 v[86:89], v[166:169], v[214:217], v[86:89]
	v_mfma_f32_16x16x32_bf16 v[82:85], v[170:173], v[210:213], v[82:85]
	v_mfma_f32_16x16x32_bf16 v[82:85], v[174:177], v[214:217], v[82:85]
	v_mfma_f32_16x16x32_bf16 v[70:73], v[162:165], v[230:233], v[70:73]
	v_mfma_f32_16x16x32_bf16 v[70:73], v[166:169], v[234:237], v[70:73]
	v_mfma_f32_16x16x32_bf16 v[66:69], v[170:173], v[230:233], v[66:69]
	v_mfma_f32_16x16x32_bf16 v[66:69], v[174:177], v[234:237], v[66:69]
	s_setprio 0
	s_barrier
	s_add_i32 s30, s31, s13
	v_lshl_add_u64 v[140:141], s[54:55], 0, v[194:195]
	s_mov_b32 m0, s30
	ds_read_b128 v[178:181], v145 offset:16384
	ds_read_b128 v[182:185], v145 offset:17408
	ds_read_b128 v[186:189], v145 offset:18432
	ds_read_b128 v[190:193], v145 offset:19456
	ds_read_b128 v[210:213], v145 offset:20480
	ds_read_b128 v[214:217], v145 offset:21504
	ds_read_b128 v[230:233], v145 offset:22528
	ds_read_b128 v[234:237], v145 offset:23552
	global_load_lds_dwordx4 v[140:141], off
	s_add_i32 m0, s30, 0x2000
	s_add_u32 s30, s54, 0x80000
	v_lshl_add_u64 v[218:219], s[54:55], 0, v[134:135]
	s_addc_u32 s31, s55, 0
	s_add_i32 s29, s29, s13
	global_load_lds_dwordx4 v[218:219], off
	v_lshl_add_u64 v[238:239], s[30:31], 0, v[194:195]
	s_mov_b32 m0, s29
	v_lshl_add_u64 v[240:241], vcc, 0, v[132:133]
	global_load_lds_dwordx4 v[238:239], off
	v_lshl_add_u64 v[238:239], s[30:31], 0, v[134:135]
	s_add_i32 m0, s29, 0x2000
	s_nop 0
	global_load_lds_dwordx4 v[238:239], off
	v_lshl_add_u64 v[238:239], vcc, 0, v[130:131]
	s_mov_b32 m0, s14
	s_nop 0
	global_load_lds_dwordx4 v[238:239], off
	s_mov_b32 m0, s15
	s_nop 0
	global_load_lds_dwordx4 v[240:241], off
	s_waitcnt vmcnt(8)
	s_waitcnt lgkmcnt(0)
	s_barrier
	s_setprio 1
	s_waitcnt lgkmcnt(0)
	v_mfma_f32_16x16x32_bf16 v[62:65], v[146:149], v[178:181], v[62:65]
	v_mfma_f32_16x16x32_bf16 v[62:65], v[150:153], v[182:185], v[62:65]
	v_mfma_f32_16x16x32_bf16 v[58:61], v[154:157], v[178:181], v[58:61]
	v_mfma_f32_16x16x32_bf16 v[58:61], v[158:161], v[182:185], v[58:61]
	v_mfma_f32_16x16x32_bf16 v[46:49], v[146:149], v[186:189], v[46:49]
	v_mfma_f32_16x16x32_bf16 v[46:49], v[150:153], v[190:193], v[46:49]
	v_mfma_f32_16x16x32_bf16 v[42:45], v[154:157], v[186:189], v[42:45]
	v_mfma_f32_16x16x32_bf16 v[42:45], v[158:161], v[190:193], v[42:45]
	v_mfma_f32_16x16x32_bf16 v[30:33], v[146:149], v[210:213], v[30:33]
	v_mfma_f32_16x16x32_bf16 v[30:33], v[150:153], v[214:217], v[30:33]
	v_mfma_f32_16x16x32_bf16 v[26:29], v[154:157], v[210:213], v[26:29]
	v_mfma_f32_16x16x32_bf16 v[26:29], v[158:161], v[214:217], v[26:29]
	v_mfma_f32_16x16x32_bf16 v[14:17], v[146:149], v[230:233], v[14:17]
	v_mfma_f32_16x16x32_bf16 v[14:17], v[150:153], v[234:237], v[14:17]
	v_mfma_f32_16x16x32_bf16 v[10:13], v[154:157], v[230:233], v[10:13]
	v_mfma_f32_16x16x32_bf16 v[10:13], v[158:161], v[234:237], v[10:13]
	s_setprio 0
	s_setprio 1
	v_mfma_f32_16x16x32_bf16 v[54:57], v[162:165], v[178:181], v[54:57]
	v_mfma_f32_16x16x32_bf16 v[54:57], v[166:169], v[182:185], v[54:57]
	v_mfma_f32_16x16x32_bf16 v[50:53], v[170:173], v[178:181], v[50:53]
	v_mfma_f32_16x16x32_bf16 v[50:53], v[174:177], v[182:185], v[50:53]
	v_mfma_f32_16x16x32_bf16 v[38:41], v[162:165], v[186:189], v[38:41]
	v_mfma_f32_16x16x32_bf16 v[38:41], v[166:169], v[190:193], v[38:41]
	v_mfma_f32_16x16x32_bf16 v[34:37], v[170:173], v[186:189], v[34:37]
	v_mfma_f32_16x16x32_bf16 v[34:37], v[174:177], v[190:193], v[34:37]
	v_mfma_f32_16x16x32_bf16 v[22:25], v[162:165], v[210:213], v[22:25]
	v_mfma_f32_16x16x32_bf16 v[22:25], v[166:169], v[214:217], v[22:25]
	v_mfma_f32_16x16x32_bf16 v[18:21], v[170:173], v[210:213], v[18:21]
	v_mfma_f32_16x16x32_bf16 v[18:21], v[174:177], v[214:217], v[18:21]
	v_mfma_f32_16x16x32_bf16 v[6:9], v[162:165], v[230:233], v[6:9]
	v_mfma_f32_16x16x32_bf16 v[6:9], v[166:169], v[234:237], v[6:9]
	v_mfma_f32_16x16x32_bf16 v[2:5], v[170:173], v[230:233], v[2:5]
	v_mfma_f32_16x16x32_bf16 v[2:5], v[174:177], v[234:237], v[2:5]
	s_setprio 0
	s_barrier
	s_add_i32 s29, 0, 0x18000
	s_add_i32 s45, 0, 0x1c000
	v_add_u32_e32 v158, s29, v143
	v_add_u32_e32 v174, s45, v143
	ds_read_b128 v[146:149], v158
	ds_read_b128 v[150:153], v158 offset:1024
	ds_read_b128 v[154:157], v158 offset:2048
	ds_read_b128 v[158:161], v158 offset:3072
	ds_read_b128 v[162:165], v174
	ds_read_b128 v[166:169], v174 offset:1024
	ds_read_b128 v[170:173], v174 offset:2048
	ds_read_b128 v[174:177], v174 offset:3072
	s_add_u32 s30, vcc_lo, 0x80000
	s_addc_u32 s31, vcc_hi, 0
	s_mov_b32 m0, s16
	v_lshl_add_u64 v[242:243], s[30:31], 0, v[130:131]
	ds_read_b128 v[178:181], v145 offset:32768
	ds_read_b128 v[182:185], v145 offset:33792
	ds_read_b128 v[186:189], v145 offset:34816
	ds_read_b128 v[190:193], v145 offset:35840
	ds_read_b128 v[210:213], v145 offset:36864
	ds_read_b128 v[214:217], v145 offset:37888
	ds_read_b128 v[230:233], v145 offset:38912
	ds_read_b128 v[234:237], v145 offset:39936
	global_load_lds_dwordx4 v[242:243], off
	v_lshl_add_u64 v[242:243], s[30:31], 0, v[132:133]
	s_mov_b32 m0, s17
	s_nop 0
	global_load_lds_dwordx4 v[242:243], off
	s_waitcnt vmcnt(8)
	s_waitcnt lgkmcnt(0)
	s_barrier
	s_setprio 1
	s_waitcnt lgkmcnt(0)
	v_mfma_f32_16x16x32_bf16 v[126:129], v[146:149], v[178:181], v[126:129]
	v_mfma_f32_16x16x32_bf16 v[126:129], v[150:153], v[182:185], v[126:129]
	v_mfma_f32_16x16x32_bf16 v[122:125], v[154:157], v[178:181], v[122:125]
	v_mfma_f32_16x16x32_bf16 v[122:125], v[158:161], v[182:185], v[122:125]
	v_mfma_f32_16x16x32_bf16 v[110:113], v[146:149], v[186:189], v[110:113]
	v_mfma_f32_16x16x32_bf16 v[110:113], v[150:153], v[190:193], v[110:113]
	v_mfma_f32_16x16x32_bf16 v[106:109], v[154:157], v[186:189], v[106:109]
	v_mfma_f32_16x16x32_bf16 v[106:109], v[158:161], v[190:193], v[106:109]
	v_mfma_f32_16x16x32_bf16 v[94:97], v[146:149], v[210:213], v[94:97]
	v_mfma_f32_16x16x32_bf16 v[94:97], v[150:153], v[214:217], v[94:97]
	v_mfma_f32_16x16x32_bf16 v[90:93], v[154:157], v[210:213], v[90:93]
	v_mfma_f32_16x16x32_bf16 v[90:93], v[158:161], v[214:217], v[90:93]
	v_mfma_f32_16x16x32_bf16 v[78:81], v[146:149], v[230:233], v[78:81]
	v_mfma_f32_16x16x32_bf16 v[78:81], v[150:153], v[234:237], v[78:81]
	v_mfma_f32_16x16x32_bf16 v[74:77], v[154:157], v[230:233], v[74:77]
	v_mfma_f32_16x16x32_bf16 v[74:77], v[158:161], v[234:237], v[74:77]
	s_setprio 0
	s_setprio 1
	v_mfma_f32_16x16x32_bf16 v[118:121], v[162:165], v[178:181], v[118:121]
	v_mfma_f32_16x16x32_bf16 v[118:121], v[166:169], v[182:185], v[118:121]
	v_mfma_f32_16x16x32_bf16 v[114:117], v[170:173], v[178:181], v[114:117]
	v_mfma_f32_16x16x32_bf16 v[114:117], v[174:177], v[182:185], v[114:117]
	v_mfma_f32_16x16x32_bf16 v[102:105], v[162:165], v[186:189], v[102:105]
	v_mfma_f32_16x16x32_bf16 v[102:105], v[166:169], v[190:193], v[102:105]
	v_mfma_f32_16x16x32_bf16 v[98:101], v[170:173], v[186:189], v[98:101]
	v_mfma_f32_16x16x32_bf16 v[98:101], v[174:177], v[190:193], v[98:101]
	v_mfma_f32_16x16x32_bf16 v[86:89], v[162:165], v[210:213], v[86:89]
	v_mfma_f32_16x16x32_bf16 v[86:89], v[166:169], v[214:217], v[86:89]
	v_mfma_f32_16x16x32_bf16 v[82:85], v[170:173], v[210:213], v[82:85]
	v_mfma_f32_16x16x32_bf16 v[82:85], v[174:177], v[214:217], v[82:85]
	v_mfma_f32_16x16x32_bf16 v[70:73], v[162:165], v[230:233], v[70:73]
	v_mfma_f32_16x16x32_bf16 v[70:73], v[166:169], v[234:237], v[70:73]
	v_mfma_f32_16x16x32_bf16 v[66:69], v[170:173], v[230:233], v[66:69]
	v_mfma_f32_16x16x32_bf16 v[66:69], v[174:177], v[234:237], v[66:69]
	s_setprio 0
	s_barrier
	s_add_i32 s29, s29, s13
	v_lshl_add_u64 v[140:141], v[140:141], 0, s[56:57]
	s_mov_b32 m0, s29
	ds_read_b128 v[178:181], v145 offset:49152
	ds_read_b128 v[182:185], v145 offset:50176
	ds_read_b128 v[186:189], v145 offset:51200
	ds_read_b128 v[190:193], v145 offset:52224
	ds_read_b128 v[210:213], v145 offset:53248
	ds_read_b128 v[214:217], v145 offset:54272
	ds_read_b128 v[230:233], v145 offset:55296
	ds_read_b128 v[234:237], v145 offset:56320
	global_load_lds_dwordx4 v[140:141], off
	s_add_i32 m0, s29, 0x2000
	s_add_u32 s30, s54, 0x80080
	v_lshl_add_u64 v[140:141], v[218:219], 0, s[56:57]
	s_addc_u32 s31, s55, 0
	s_add_i32 s29, s45, s13
	global_load_lds_dwordx4 v[140:141], off
	v_lshl_add_u64 v[140:141], s[30:31], 0, v[194:195]
	s_mov_b32 m0, s29
	s_nop 0
	global_load_lds_dwordx4 v[140:141], off
	v_lshl_add_u64 v[140:141], s[30:31], 0, v[134:135]
	s_add_i32 m0, s29, 0x2000
	s_nop 0
	global_load_lds_dwordx4 v[140:141], off
	v_lshl_add_u64 v[140:141], v[238:239], 0, s[56:57]
	s_mov_b32 m0, s18
	s_nop 0
	global_load_lds_dwordx4 v[140:141], off
	v_lshl_add_u64 v[140:141], v[240:241], 0, s[56:57]
	s_mov_b32 m0, s19
	s_nop 0
	global_load_lds_dwordx4 v[140:141], off
	s_waitcnt vmcnt(8)
	s_waitcnt lgkmcnt(0)
	s_barrier
	s_setprio 1
	s_waitcnt lgkmcnt(0)
	v_mfma_f32_16x16x32_bf16 v[62:65], v[146:149], v[178:181], v[62:65]
	v_mfma_f32_16x16x32_bf16 v[62:65], v[150:153], v[182:185], v[62:65]
	v_mfma_f32_16x16x32_bf16 v[58:61], v[154:157], v[178:181], v[58:61]
	v_mfma_f32_16x16x32_bf16 v[58:61], v[158:161], v[182:185], v[58:61]
	v_mfma_f32_16x16x32_bf16 v[46:49], v[146:149], v[186:189], v[46:49]
	v_mfma_f32_16x16x32_bf16 v[46:49], v[150:153], v[190:193], v[46:49]
	v_mfma_f32_16x16x32_bf16 v[42:45], v[154:157], v[186:189], v[42:45]
	v_mfma_f32_16x16x32_bf16 v[42:45], v[158:161], v[190:193], v[42:45]
	v_mfma_f32_16x16x32_bf16 v[30:33], v[146:149], v[210:213], v[30:33]
	v_mfma_f32_16x16x32_bf16 v[30:33], v[150:153], v[214:217], v[30:33]
	v_mfma_f32_16x16x32_bf16 v[26:29], v[154:157], v[210:213], v[26:29]
	v_mfma_f32_16x16x32_bf16 v[26:29], v[158:161], v[214:217], v[26:29]
	v_mfma_f32_16x16x32_bf16 v[14:17], v[146:149], v[230:233], v[14:17]
	v_mfma_f32_16x16x32_bf16 v[14:17], v[150:153], v[234:237], v[14:17]
	v_mfma_f32_16x16x32_bf16 v[10:13], v[154:157], v[230:233], v[10:13]
	v_mfma_f32_16x16x32_bf16 v[10:13], v[158:161], v[234:237], v[10:13]
	s_setprio 0
	s_setprio 1
	v_mfma_f32_16x16x32_bf16 v[54:57], v[162:165], v[178:181], v[54:57]
	v_mfma_f32_16x16x32_bf16 v[54:57], v[166:169], v[182:185], v[54:57]
	v_mfma_f32_16x16x32_bf16 v[50:53], v[170:173], v[178:181], v[50:53]
	v_mfma_f32_16x16x32_bf16 v[50:53], v[174:177], v[182:185], v[50:53]
	v_mfma_f32_16x16x32_bf16 v[38:41], v[162:165], v[186:189], v[38:41]
	v_mfma_f32_16x16x32_bf16 v[38:41], v[166:169], v[190:193], v[38:41]
	v_mfma_f32_16x16x32_bf16 v[34:37], v[170:173], v[186:189], v[34:37]
	v_mfma_f32_16x16x32_bf16 v[34:37], v[174:177], v[190:193], v[34:37]
	v_mfma_f32_16x16x32_bf16 v[22:25], v[162:165], v[210:213], v[22:25]
	v_mfma_f32_16x16x32_bf16 v[22:25], v[166:169], v[214:217], v[22:25]
	v_mfma_f32_16x16x32_bf16 v[18:21], v[170:173], v[210:213], v[18:21]
	v_mfma_f32_16x16x32_bf16 v[18:21], v[174:177], v[214:217], v[18:21]
	v_mfma_f32_16x16x32_bf16 v[6:9], v[162:165], v[230:233], v[6:9]
	v_mfma_f32_16x16x32_bf16 v[6:9], v[166:169], v[234:237], v[6:9]
	v_mfma_f32_16x16x32_bf16 v[2:5], v[170:173], v[230:233], v[2:5]
	v_mfma_f32_16x16x32_bf16 v[2:5], v[174:177], v[234:237], v[2:5]
	s_setprio 0
	s_barrier
	s_add_i32 s28, s28, 2
	s_add_u32 s26, s26, 0x100
	s_addc_u32 s27, s27, 0
	s_add_u32 s90, s90, 0x100
	s_addc_u32 s91, s91, 0
	s_cmp_gt_u32 s28, 29
	s_cbranch_scc0 .LBB0_1609
	s_and_b64 vcc, exec, s[36:37]
	s_cbranch_vccz .LBB0_1612
	s_barrier

.LBB0_1688:
	s_add_u32 s28, s90, 0xffe00080
	s_addc_u32 s29, s91, -1
	s_add_i32 s30, 0, 0x10000
	s_cmpk_eq_i32 s27, 0x7c
	s_cselect_b32 vcc_hi, s21, s29
	s_cselect_b32 vcc_lo, s22, s28
	v_add_u32_e32 v140, s30, v143
	s_cselect_b32 s55, s23, s26
	s_cselect_b32 s54, s24, s25
	s_add_i32 s31, 0, 0x14000
	ds_read_b128 v[146:149], v140
	ds_read_b128 v[150:153], v140 offset:1024
	ds_read_b128 v[154:157], v140 offset:2048
	ds_read_b128 v[158:161], v140 offset:3072
	v_add_u32_e32 v140, s31, v143
	ds_read_b128 v[162:165], v140
	ds_read_b128 v[166:169], v140 offset:1024
	ds_read_b128 v[170:173], v140 offset:2048
	ds_read_b128 v[174:177], v140 offset:3072
	v_lshl_add_u64 v[140:141], s[90:91], 0, v[138:139]
	s_add_i32 m0, s13, 0xc000
	ds_read_b128 v[178:181], v145
	ds_read_b128 v[182:185], v145 offset:1024
	ds_read_b128 v[186:189], v145 offset:2048
	ds_read_b128 v[190:193], v145 offset:3072
	ds_read_b128 v[210:213], v145 offset:4096
	ds_read_b128 v[214:217], v145 offset:5120
	ds_read_b128 v[230:233], v145 offset:6144
	ds_read_b128 v[234:237], v145 offset:7168
	global_load_lds_dwordx4 v[140:141], off
	v_lshl_add_u64 v[140:141], s[90:91], 0, v[136:137]
	s_add_i32 m0, s13, 0xe000
	s_nop 0
	global_load_lds_dwordx4 v[140:141], off
	s_waitcnt vmcnt(8)
	s_waitcnt lgkmcnt(0)
	s_barrier
	s_setprio 1
	s_waitcnt lgkmcnt(0)
	v_mfma_f32_16x16x32_bf16 v[126:129], v[146:149], v[178:181], v[126:129]
	v_mfma_f32_16x16x32_bf16 v[126:129], v[150:153], v[182:185], v[126:129]
	v_mfma_f32_16x16x32_bf16 v[122:125], v[154:157], v[178:181], v[122:125]
	v_mfma_f32_16x16x32_bf16 v[122:125], v[158:161], v[182:185], v[122:125]
	v_mfma_f32_16x16x32_bf16 v[118:121], v[146:149], v[186:189], v[118:121]
	v_mfma_f32_16x16x32_bf16 v[118:121], v[150:153], v[190:193], v[118:121]
	v_mfma_f32_16x16x32_bf16 v[110:113], v[154:157], v[186:189], v[110:113]
	v_mfma_f32_16x16x32_bf16 v[110:113], v[158:161], v[190:193], v[110:113]
	v_mfma_f32_16x16x32_bf16 v[102:105], v[146:149], v[210:213], v[102:105]
	v_mfma_f32_16x16x32_bf16 v[102:105], v[150:153], v[214:217], v[102:105]
	v_mfma_f32_16x16x32_bf16 v[94:97], v[154:157], v[210:213], v[94:97]
	v_mfma_f32_16x16x32_bf16 v[94:97], v[158:161], v[214:217], v[94:97]
	v_mfma_f32_16x16x32_bf16 v[86:89], v[146:149], v[230:233], v[86:89]
	v_mfma_f32_16x16x32_bf16 v[86:89], v[150:153], v[234:237], v[86:89]
	v_mfma_f32_16x16x32_bf16 v[78:81], v[154:157], v[230:233], v[78:81]
	v_mfma_f32_16x16x32_bf16 v[78:81], v[158:161], v[234:237], v[78:81]
	s_setprio 0
	s_setprio 1
	v_mfma_f32_16x16x32_bf16 v[114:117], v[162:165], v[178:181], v[114:117]
	v_mfma_f32_16x16x32_bf16 v[114:117], v[166:169], v[182:185], v[114:117]
	v_mfma_f32_16x16x32_bf16 v[106:109], v[170:173], v[178:181], v[106:109]
	v_mfma_f32_16x16x32_bf16 v[106:109], v[174:177], v[182:185], v[106:109]
	v_mfma_f32_16x16x32_bf16 v[98:101], v[162:165], v[186:189], v[98:101]
	v_mfma_f32_16x16x32_bf16 v[98:101], v[166:169], v[190:193], v[98:101]
	v_mfma_f32_16x16x32_bf16 v[90:93], v[170:173], v[186:189], v[90:93]
	v_mfma_f32_16x16x32_bf16 v[90:93], v[174:177], v[190:193], v[90:93]
	v_mfma_f32_16x16x32_bf16 v[82:85], v[162:165], v[210:213], v[82:85]
	v_mfma_f32_16x16x32_bf16 v[82:85], v[166:169], v[214:217], v[82:85]
	v_mfma_f32_16x16x32_bf16 v[74:77], v[170:173], v[210:213], v[74:77]
	v_mfma_f32_16x16x32_bf16 v[74:77], v[174:177], v[214:217], v[74:77]
	v_mfma_f32_16x16x32_bf16 v[70:73], v[162:165], v[230:233], v[70:73]
	v_mfma_f32_16x16x32_bf16 v[70:73], v[166:169], v[234:237], v[70:73]
	v_mfma_f32_16x16x32_bf16 v[66:69], v[170:173], v[230:233], v[66:69]
	v_mfma_f32_16x16x32_bf16 v[66:69], v[174:177], v[234:237], v[66:69]
	s_setprio 0
	s_barrier
	s_add_i32 s28, s30, s12
	v_lshl_add_u64 v[140:141], s[54:55], 0, v[194:195]
	s_mov_b32 m0, s28
	ds_read_b128 v[178:181], v145 offset:16384
	ds_read_b128 v[182:185], v145 offset:17408
	ds_read_b128 v[186:189], v145 offset:18432
	ds_read_b128 v[190:193], v145 offset:19456
	ds_read_b128 v[210:213], v145 offset:20480
	ds_read_b128 v[214:217], v145 offset:21504
	ds_read_b128 v[230:233], v145 offset:22528
	ds_read_b128 v[234:237], v145 offset:23552
	global_load_lds_dwordx4 v[140:141], off
	s_add_i32 m0, s28, 0x2000
	s_add_u32 s28, s54, 0x200000
	v_lshl_add_u64 v[218:219], s[54:55], 0, v[134:135]
	s_addc_u32 s29, s55, 0
	s_add_i32 s30, s31, s12
	global_load_lds_dwordx4 v[218:219], off
	v_lshl_add_u64 v[238:239], s[28:29], 0, v[194:195]
	s_mov_b32 m0, s30
	v_lshl_add_u64 v[240:241], vcc, 0, v[132:133]
	global_load_lds_dwordx4 v[238:239], off
	v_lshl_add_u64 v[238:239], s[28:29], 0, v[134:135]
	s_add_i32 m0, s30, 0x2000
	s_nop 0
	global_load_lds_dwordx4 v[238:239], off
	v_lshl_add_u64 v[238:239], vcc, 0, v[130:131]
	s_mov_b32 m0, s13
	s_nop 0
	global_load_lds_dwordx4 v[238:239], off
	s_mov_b32 m0, s14
	s_nop 0
	global_load_lds_dwordx4 v[240:241], off
	s_waitcnt vmcnt(8)
	s_waitcnt lgkmcnt(0)
	s_barrier
	s_setprio 1
	s_waitcnt lgkmcnt(0)
	v_mfma_f32_16x16x32_bf16 v[62:65], v[146:149], v[178:181], v[62:65]
	v_mfma_f32_16x16x32_bf16 v[62:65], v[150:153], v[182:185], v[62:65]
	v_mfma_f32_16x16x32_bf16 v[58:61], v[154:157], v[178:181], v[58:61]
	v_mfma_f32_16x16x32_bf16 v[58:61], v[158:161], v[182:185], v[58:61]
	v_mfma_f32_16x16x32_bf16 v[54:57], v[146:149], v[186:189], v[54:57]
	v_mfma_f32_16x16x32_bf16 v[54:57], v[150:153], v[190:193], v[54:57]
	v_mfma_f32_16x16x32_bf16 v[46:49], v[154:157], v[186:189], v[46:49]
	v_mfma_f32_16x16x32_bf16 v[46:49], v[158:161], v[190:193], v[46:49]
	v_mfma_f32_16x16x32_bf16 v[38:41], v[146:149], v[210:213], v[38:41]
	v_mfma_f32_16x16x32_bf16 v[38:41], v[150:153], v[214:217], v[38:41]
	v_mfma_f32_16x16x32_bf16 v[30:33], v[154:157], v[210:213], v[30:33]
	v_mfma_f32_16x16x32_bf16 v[30:33], v[158:161], v[214:217], v[30:33]
	v_mfma_f32_16x16x32_bf16 v[22:25], v[146:149], v[230:233], v[22:25]
	v_mfma_f32_16x16x32_bf16 v[22:25], v[150:153], v[234:237], v[22:25]
	v_mfma_f32_16x16x32_bf16 v[14:17], v[154:157], v[230:233], v[14:17]
	v_mfma_f32_16x16x32_bf16 v[14:17], v[158:161], v[234:237], v[14:17]
	s_setprio 0
	s_setprio 1
	v_mfma_f32_16x16x32_bf16 v[50:53], v[162:165], v[178:181], v[50:53]
	v_mfma_f32_16x16x32_bf16 v[50:53], v[166:169], v[182:185], v[50:53]
	v_mfma_f32_16x16x32_bf16 v[42:45], v[170:173], v[178:181], v[42:45]
	v_mfma_f32_16x16x32_bf16 v[42:45], v[174:177], v[182:185], v[42:45]
	v_mfma_f32_16x16x32_bf16 v[34:37], v[162:165], v[186:189], v[34:37]
	v_mfma_f32_16x16x32_bf16 v[34:37], v[166:169], v[190:193], v[34:37]
	v_mfma_f32_16x16x32_bf16 v[26:29], v[170:173], v[186:189], v[26:29]
	v_mfma_f32_16x16x32_bf16 v[26:29], v[174:177], v[190:193], v[26:29]
	v_mfma_f32_16x16x32_bf16 v[18:21], v[162:165], v[210:213], v[18:21]
	v_mfma_f32_16x16x32_bf16 v[18:21], v[166:169], v[214:217], v[18:21]
	v_mfma_f32_16x16x32_bf16 v[10:13], v[170:173], v[210:213], v[10:13]
	v_mfma_f32_16x16x32_bf16 v[10:13], v[174:177], v[214:217], v[10:13]
	v_mfma_f32_16x16x32_bf16 v[6:9], v[162:165], v[230:233], v[6:9]
	v_mfma_f32_16x16x32_bf16 v[6:9], v[166:169], v[234:237], v[6:9]
	v_mfma_f32_16x16x32_bf16 v[2:5], v[170:173], v[230:233], v[2:5]
	v_mfma_f32_16x16x32_bf16 v[2:5], v[174:177], v[234:237], v[2:5]
	s_setprio 0
	s_barrier
	s_add_i32 s30, 0, 0x18000
	s_add_i32 s31, 0, 0x1c000
	v_add_u32_e32 v158, s30, v143
	v_add_u32_e32 v174, s31, v143
	ds_read_b128 v[146:149], v158
	ds_read_b128 v[150:153], v158 offset:1024
	ds_read_b128 v[154:157], v158 offset:2048
	ds_read_b128 v[158:161], v158 offset:3072
	ds_read_b128 v[162:165], v174
	ds_read_b128 v[166:169], v174 offset:1024
	ds_read_b128 v[170:173], v174 offset:2048
	ds_read_b128 v[174:177], v174 offset:3072
	s_add_u32 s28, vcc_lo, 0x200000
	s_addc_u32 s29, vcc_hi, 0
	s_mov_b32 m0, s15
	v_lshl_add_u64 v[242:243], s[28:29], 0, v[130:131]
	ds_read_b128 v[178:181], v145 offset:32768
	ds_read_b128 v[182:185], v145 offset:33792
	ds_read_b128 v[186:189], v145 offset:34816
	ds_read_b128 v[190:193], v145 offset:35840
	ds_read_b128 v[210:213], v145 offset:36864
	ds_read_b128 v[214:217], v145 offset:37888
	ds_read_b128 v[230:233], v145 offset:38912
	ds_read_b128 v[234:237], v145 offset:39936
	global_load_lds_dwordx4 v[242:243], off
	v_lshl_add_u64 v[242:243], s[28:29], 0, v[132:133]
	s_mov_b32 m0, s16
	s_nop 0
	global_load_lds_dwordx4 v[242:243], off
	s_waitcnt vmcnt(8)
	s_waitcnt lgkmcnt(0)
	s_barrier
	s_setprio 1
	s_waitcnt lgkmcnt(0)
	v_mfma_f32_16x16x32_bf16 v[126:129], v[146:149], v[178:181], v[126:129]
	v_mfma_f32_16x16x32_bf16 v[126:129], v[150:153], v[182:185], v[126:129]
	v_mfma_f32_16x16x32_bf16 v[122:125], v[154:157], v[178:181], v[122:125]
	v_mfma_f32_16x16x32_bf16 v[122:125], v[158:161], v[182:185], v[122:125]
	v_mfma_f32_16x16x32_bf16 v[118:121], v[146:149], v[186:189], v[118:121]
	v_mfma_f32_16x16x32_bf16 v[118:121], v[150:153], v[190:193], v[118:121]
	v_mfma_f32_16x16x32_bf16 v[110:113], v[154:157], v[186:189], v[110:113]
	v_mfma_f32_16x16x32_bf16 v[110:113], v[158:161], v[190:193], v[110:113]
	v_mfma_f32_16x16x32_bf16 v[102:105], v[146:149], v[210:213], v[102:105]
	v_mfma_f32_16x16x32_bf16 v[102:105], v[150:153], v[214:217], v[102:105]
	v_mfma_f32_16x16x32_bf16 v[94:97], v[154:157], v[210:213], v[94:97]
	v_mfma_f32_16x16x32_bf16 v[94:97], v[158:161], v[214:217], v[94:97]
	v_mfma_f32_16x16x32_bf16 v[86:89], v[146:149], v[230:233], v[86:89]
	v_mfma_f32_16x16x32_bf16 v[86:89], v[150:153], v[234:237], v[86:89]
	v_mfma_f32_16x16x32_bf16 v[78:81], v[154:157], v[230:233], v[78:81]
	v_mfma_f32_16x16x32_bf16 v[78:81], v[158:161], v[234:237], v[78:81]
	s_setprio 0
	s_setprio 1
	v_mfma_f32_16x16x32_bf16 v[114:117], v[162:165], v[178:181], v[114:117]
	v_mfma_f32_16x16x32_bf16 v[114:117], v[166:169], v[182:185], v[114:117]
	v_mfma_f32_16x16x32_bf16 v[106:109], v[170:173], v[178:181], v[106:109]
	v_mfma_f32_16x16x32_bf16 v[106:109], v[174:177], v[182:185], v[106:109]
	v_mfma_f32_16x16x32_bf16 v[98:101], v[162:165], v[186:189], v[98:101]
	v_mfma_f32_16x16x32_bf16 v[98:101], v[166:169], v[190:193], v[98:101]
	v_mfma_f32_16x16x32_bf16 v[90:93], v[170:173], v[186:189], v[90:93]
	v_mfma_f32_16x16x32_bf16 v[90:93], v[174:177], v[190:193], v[90:93]
	v_mfma_f32_16x16x32_bf16 v[82:85], v[162:165], v[210:213], v[82:85]
	v_mfma_f32_16x16x32_bf16 v[82:85], v[166:169], v[214:217], v[82:85]
	v_mfma_f32_16x16x32_bf16 v[74:77], v[170:173], v[210:213], v[74:77]
	v_mfma_f32_16x16x32_bf16 v[74:77], v[174:177], v[214:217], v[74:77]
	v_mfma_f32_16x16x32_bf16 v[70:73], v[162:165], v[230:233], v[70:73]
	v_mfma_f32_16x16x32_bf16 v[70:73], v[166:169], v[234:237], v[70:73]
	v_mfma_f32_16x16x32_bf16 v[66:69], v[170:173], v[230:233], v[66:69]
	v_mfma_f32_16x16x32_bf16 v[66:69], v[174:177], v[234:237], v[66:69]
	s_setprio 0
	s_barrier
	s_add_i32 s28, s30, s12
	v_lshl_add_u64 v[140:141], v[140:141], 0, s[56:57]
	s_mov_b32 m0, s28
	ds_read_b128 v[178:181], v145 offset:49152
	ds_read_b128 v[182:185], v145 offset:50176
	ds_read_b128 v[186:189], v145 offset:51200
	ds_read_b128 v[190:193], v145 offset:52224
	ds_read_b128 v[210:213], v145 offset:53248
	ds_read_b128 v[214:217], v145 offset:54272
	ds_read_b128 v[230:233], v145 offset:55296
	ds_read_b128 v[234:237], v145 offset:56320
	global_load_lds_dwordx4 v[140:141], off
	s_add_i32 m0, s28, 0x2000
	s_add_u32 s28, s54, 0x200080
	v_lshl_add_u64 v[140:141], v[218:219], 0, s[56:57]
	s_addc_u32 s29, s55, 0
	s_add_i32 s30, s31, s12
	global_load_lds_dwordx4 v[140:141], off
	v_lshl_add_u64 v[140:141], s[28:29], 0, v[194:195]
	s_mov_b32 m0, s30
	s_nop 0
	global_load_lds_dwordx4 v[140:141], off
	v_lshl_add_u64 v[140:141], s[28:29], 0, v[134:135]
	s_add_i32 m0, s30, 0x2000
	s_nop 0
	global_load_lds_dwordx4 v[140:141], off
	v_lshl_add_u64 v[140:141], v[238:239], 0, s[56:57]
	s_mov_b32 m0, s17
	s_nop 0
	global_load_lds_dwordx4 v[140:141], off
	v_lshl_add_u64 v[140:141], v[240:241], 0, s[56:57]
	s_mov_b32 m0, s18
	s_nop 0
	global_load_lds_dwordx4 v[140:141], off
	s_waitcnt vmcnt(8)
	s_waitcnt lgkmcnt(0)
	s_barrier
	s_setprio 1
	s_waitcnt lgkmcnt(0)
	v_mfma_f32_16x16x32_bf16 v[62:65], v[146:149], v[178:181], v[62:65]
	v_mfma_f32_16x16x32_bf16 v[62:65], v[150:153], v[182:185], v[62:65]
	v_mfma_f32_16x16x32_bf16 v[58:61], v[154:157], v[178:181], v[58:61]
	v_mfma_f32_16x16x32_bf16 v[58:61], v[158:161], v[182:185], v[58:61]
	v_mfma_f32_16x16x32_bf16 v[54:57], v[146:149], v[186:189], v[54:57]
	v_mfma_f32_16x16x32_bf16 v[54:57], v[150:153], v[190:193], v[54:57]
	v_mfma_f32_16x16x32_bf16 v[46:49], v[154:157], v[186:189], v[46:49]
	v_mfma_f32_16x16x32_bf16 v[46:49], v[158:161], v[190:193], v[46:49]
	v_mfma_f32_16x16x32_bf16 v[38:41], v[146:149], v[210:213], v[38:41]
	v_mfma_f32_16x16x32_bf16 v[38:41], v[150:153], v[214:217], v[38:41]
	v_mfma_f32_16x16x32_bf16 v[30:33], v[154:157], v[210:213], v[30:33]
	v_mfma_f32_16x16x32_bf16 v[30:33], v[158:161], v[214:217], v[30:33]
	v_mfma_f32_16x16x32_bf16 v[22:25], v[146:149], v[230:233], v[22:25]
	v_mfma_f32_16x16x32_bf16 v[22:25], v[150:153], v[234:237], v[22:25]
	v_mfma_f32_16x16x32_bf16 v[14:17], v[154:157], v[230:233], v[14:17]
	v_mfma_f32_16x16x32_bf16 v[14:17], v[158:161], v[234:237], v[14:17]
	s_setprio 0
	s_setprio 1
	v_mfma_f32_16x16x32_bf16 v[50:53], v[162:165], v[178:181], v[50:53]
	v_mfma_f32_16x16x32_bf16 v[50:53], v[166:169], v[182:185], v[50:53]
	v_mfma_f32_16x16x32_bf16 v[42:45], v[170:173], v[178:181], v[42:45]
	v_mfma_f32_16x16x32_bf16 v[42:45], v[174:177], v[182:185], v[42:45]
	v_mfma_f32_16x16x32_bf16 v[34:37], v[162:165], v[186:189], v[34:37]
	v_mfma_f32_16x16x32_bf16 v[34:37], v[166:169], v[190:193], v[34:37]
	v_mfma_f32_16x16x32_bf16 v[26:29], v[170:173], v[186:189], v[26:29]
	v_mfma_f32_16x16x32_bf16 v[26:29], v[174:177], v[190:193], v[26:29]
	v_mfma_f32_16x16x32_bf16 v[18:21], v[162:165], v[210:213], v[18:21]
	v_mfma_f32_16x16x32_bf16 v[18:21], v[166:169], v[214:217], v[18:21]
	v_mfma_f32_16x16x32_bf16 v[10:13], v[170:173], v[210:213], v[10:13]
	v_mfma_f32_16x16x32_bf16 v[10:13], v[174:177], v[214:217], v[10:13]
	v_mfma_f32_16x16x32_bf16 v[6:9], v[162:165], v[230:233], v[6:9]
	v_mfma_f32_16x16x32_bf16 v[6:9], v[166:169], v[234:237], v[6:9]
	v_mfma_f32_16x16x32_bf16 v[2:5], v[170:173], v[230:233], v[2:5]
	v_mfma_f32_16x16x32_bf16 v[2:5], v[174:177], v[234:237], v[2:5]
	s_setprio 0
	s_barrier
	s_add_i32 s27, s27, 2
	s_add_u32 s25, s25, 0x100
	s_addc_u32 s26, s26, 0
	s_add_u32 s90, s90, 0x100
	s_addc_u32 s91, s91, 0
	s_cmpk_gt_u32 s27, 0x7d
	s_cbranch_scc0 .LBB0_1688
	s_and_b64 vcc, exec, s[52:53]
	s_cbranch_vccz .LBB0_1691
	s_barrier
